# P6 prompt items take the hand-written path (rolling state registers, no phi copies, double-buffered counted-wait loads, scalar addressing, packed f32 math in the same association as hipcc's); sample i
# speedup vs baseline: 1.0052x; 1.0052x over previous
; __device__ __forceinline__ float bf2f(unsigned b) { return __uint_as_float(b << 16); }
; __device__ __forceinline__ void act_item(int item, u16* UP, const u16* HALO, const float* sconv, const float* wconv, const float* bconv, float* out, int lane) {
;     const int rb = item / 22, cch = item - rb * 22, j0 = cch * 128 + 2 * lane;
;     float wgt[3][2], wvl[3][2], bg[2], bv[2];
; #pragma unroll
;     for (int k = 0; k < 3; ++k) { const f32x2 a = *(const f32x2*)(wconv + k * FF2 + j0), b = *(const f32x2*)(wconv + k * FF2 + FF + j0); wgt[k][0] = a.x; wgt[k][1] = a.y; wvl[k][0] = b.x; wvl[k][1] = b.y; }
;     { const f32x2 a = *(const f32x2*)(bconv + j0), b = *(const f32x2*)(bconv + FF + j0); bg[0] = a.x; bg[1] = a.y; bv[0] = b.x; bv[1] = b.y; }
;     const bool sample = rb >= 256;
;     float g2[2] = {0.f, 0.f}, g1[2] = {0.f, 0.f}, v2[2] = {0.f, 0.f}, v1[2] = {0.f, 0.f};
;     if (!sample && (rb & 31) != 0) {
;         const unsigned a = *(const unsigned*)(HALO + (size_t)((rb - 1) * 2) * FF2 + j0), b = *(const unsigned*)(HALO + (size_t)((rb - 1) * 2) * FF2 + FF + j0);
;         const unsigned c = *(const unsigned*)(HALO + (size_t)((rb - 1) * 2 + 1) * FF2 + j0), dd = *(const unsigned*)(HALO + (size_t)((rb - 1) * 2 + 1) * FF2 + FF + j0);
;         g2[0] = bf2f(a & 0xffffu); g2[1] = bf2f(a >> 16); v2[0] = bf2f(b & 0xffffu); v2[1] = bf2f(b >> 16);
;         g1[0] = bf2f(c & 0xffffu); g1[1] = bf2f(c >> 16); v1[0] = bf2f(dd & 0xffffu); v1[1] = bf2f(dd >> 16);
;     }
;     for (int tb = 0; tb < 64; tb += 16) {
;         unsigned gw[16], vw[16];
; #pragma unroll
;         for (int t = 0; t < 16; ++t) { const size_t row = (size_t)rb * 64 + tb + t; gw[t] = *(const unsigned*)(UP + row * FF2 + j0); vw[t] = *(const unsigned*)(UP + row * FF2 + FF + j0); }
.Lact_fast:
	v_lshlrev_b32_e32 v2, 1, v2
	v_add_u32_e32 v3, 0x1600, v2
	v_lshlrev_b32_e32 v1, 1, v2
	s_mul_i32 s6, s0, 0xb0000
	s_mul_hi_u32 s7, s0, 0xb0000
	s_add_u32 s64, s92, s6
	s_addc_u32 s65, s93, s7
	s_add_u32 s64, s64, 0x4300000
	s_addc_u32 s65, s65, 0
	s_mov_b64 s[66:67], s[64:65]
	s_mov_b32 s58, 0x3d372713
	s_mov_b32 s59, s58
	s_mov_b32 s60, 0xbfcc422a
	s_mov_b32 s61, s60
	s_mov_b32 s68, 0x3fb8aa3b
	s_mov_b32 s69, s68
	s_mov_b32 s82, 1.0
	s_mov_b32 s83, 1.0
	s_and_b32 s1, s0, 31
	s_cmp_eq_u32 s1, 0
	s_cbranch_scc1 .Lact_nohalo
	s_mul_i32 s6, s0, 0x5800
	s_mul_hi_u32 s7, s0, 0x5800
	s_add_u32 s6, s18, s6
	s_addc_u32 s7, s19, s7
	s_sub_u32 s6, s6, 0x5800
	s_subb_u32 s7, s7, 0
	global_load_dword v226, v2, s[6:7]
	global_load_dword v227, v3, s[6:7]
	s_add_u32 s6, s6, 0x2c00
	s_addc_u32 s7, s7, 0
	global_load_dword v228, v2, s[6:7]
	global_load_dword v229, v3, s[6:7]
	s_branch .Lact_rows
.Lact_nohalo:
	v_mov_b32_e32 v226, 0
	v_mov_b32_e32 v227, 0
	v_mov_b32_e32 v228, 0
	v_mov_b32_e32 v229, 0
.Lact_rows:
	global_load_dword v160, v2, s[64:65]
	global_load_dword v161, v3, s[64:65]
	s_add_u32 s64, s64, 0x2c00
	s_addc_u32 s65, s65, 0
	global_load_dword v162, v2, s[64:65]
	global_load_dword v163, v3, s[64:65]
	s_add_u32 s64, s64, 0x2c00
	s_addc_u32 s65, s65, 0
	global_load_dword v164, v2, s[64:65]
	global_load_dword v165, v3, s[64:65]
	s_add_u32 s64, s64, 0x2c00
	s_addc_u32 s65, s65, 0
	global_load_dword v166, v2, s[64:65]
	global_load_dword v167, v3, s[64:65]
	s_add_u32 s64, s64, 0x2c00
	s_addc_u32 s65, s65, 0
	global_load_dword v168, v2, s[64:65]
	global_load_dword v169, v3, s[64:65]
	s_add_u32 s64, s64, 0x2c00
	s_addc_u32 s65, s65, 0
	global_load_dword v170, v2, s[64:65]
	global_load_dword v171, v3, s[64:65]
	s_add_u32 s64, s64, 0x2c00
	s_addc_u32 s65, s65, 0
	global_load_dword v172, v2, s[64:65]
	global_load_dword v173, v3, s[64:65]
	s_add_u32 s64, s64, 0x2c00
	s_addc_u32 s65, s65, 0
	global_load_dword v174, v2, s[64:65]
	global_load_dword v175, v3, s[64:65]
	s_add_u32 s64, s64, 0x2c00
	s_addc_u32 s65, s65, 0
	global_load_dword v176, v2, s[64:65]
	global_load_dword v177, v3, s[64:65]
	s_add_u32 s64, s64, 0x2c00
	s_addc_u32 s65, s65, 0
	global_load_dword v178, v2, s[64:65]
	global_load_dword v179, v3, s[64:65]
	s_add_u32 s64, s64, 0x2c00
	s_addc_u32 s65, s65, 0
	global_load_dword v180, v2, s[64:65]
	global_load_dword v181, v3, s[64:65]
	s_add_u32 s64, s64, 0x2c00
	s_addc_u32 s65, s65, 0
	global_load_dword v182, v2, s[64:65]
	global_load_dword v183, v3, s[64:65]
	s_add_u32 s64, s64, 0x2c00
	s_addc_u32 s65, s65, 0
	global_load_dword v184, v2, s[64:65]
	global_load_dword v185, v3, s[64:65]
	s_add_u32 s64, s64, 0x2c00
	s_addc_u32 s65, s65, 0
	global_load_dword v186, v2, s[64:65]
	global_load_dword v187, v3, s[64:65]
	s_add_u32 s64, s64, 0x2c00
	s_addc_u32 s65, s65, 0
	global_load_dword v188, v2, s[64:65]
	global_load_dword v189, v3, s[64:65]
	s_add_u32 s64, s64, 0x2c00
	s_addc_u32 s65, s65, 0
	global_load_dword v190, v2, s[64:65]
	global_load_dword v191, v3, s[64:65]
	s_add_u32 s64, s64, 0x2c00
	s_addc_u32 s65, s65, 0
	global_load_dword v192, v2, s[64:65]
	global_load_dword v193, v3, s[64:65]
	s_add_u32 s64, s64, 0x2c00
	s_addc_u32 s65, s65, 0
	global_load_dword v194, v2, s[64:65]
	global_load_dword v195, v3, s[64:65]
	s_add_u32 s64, s64, 0x2c00
	s_addc_u32 s65, s65, 0
	global_load_dword v196, v2, s[64:65]
	global_load_dword v197, v3, s[64:65]
	s_add_u32 s64, s64, 0x2c00
	s_addc_u32 s65, s65, 0
	global_load_dword v198, v2, s[64:65]
	global_load_dword v199, v3, s[64:65]
	s_add_u32 s64, s64, 0x2c00
	s_addc_u32 s65, s65, 0
	global_load_dword v200, v2, s[64:65]
	global_load_dword v201, v3, s[64:65]
	s_add_u32 s64, s64, 0x2c00
	s_addc_u32 s65, s65, 0
	global_load_dword v202, v2, s[64:65]
	global_load_dword v203, v3, s[64:65]
	s_add_u32 s64, s64, 0x2c00
	s_addc_u32 s65, s65, 0
	global_load_dword v204, v2, s[64:65]
	global_load_dword v205, v3, s[64:65]
	s_add_u32 s64, s64, 0x2c00
	s_addc_u32 s65, s65, 0
	global_load_dword v206, v2, s[64:65]
	global_load_dword v207, v3, s[64:65]
	s_add_u32 s64, s64, 0x2c00
	s_addc_u32 s65, s65, 0
	global_load_dword v208, v2, s[64:65]
	global_load_dword v209, v3, s[64:65]
	s_add_u32 s64, s64, 0x2c00
	s_addc_u32 s65, s65, 0
	global_load_dword v210, v2, s[64:65]
	global_load_dword v211, v3, s[64:65]
	s_add_u32 s64, s64, 0x2c00
	s_addc_u32 s65, s65, 0
	global_load_dword v212, v2, s[64:65]
	global_load_dword v213, v3, s[64:65]
	s_add_u32 s64, s64, 0x2c00
	s_addc_u32 s65, s65, 0
	global_load_dword v214, v2, s[64:65]
	global_load_dword v215, v3, s[64:65]
	s_add_u32 s64, s64, 0x2c00
	s_addc_u32 s65, s65, 0
	global_load_dword v216, v2, s[64:65]
	global_load_dword v217, v3, s[64:65]
	s_add_u32 s64, s64, 0x2c00
	s_addc_u32 s65, s65, 0
	global_load_dword v218, v2, s[64:65]
	global_load_dword v219, v3, s[64:65]
	s_add_u32 s64, s64, 0x2c00
	s_addc_u32 s65, s65, 0
	global_load_dword v220, v2, s[64:65]
	global_load_dword v221, v3, s[64:65]
	s_add_u32 s64, s64, 0x2c00
	s_addc_u32 s65, s65, 0
	global_load_dword v222, v2, s[64:65]
	global_load_dword v223, v3, s[64:65]
	s_add_u32 s64, s64, 0x2c00
	s_addc_u32 s65, s65, 0
	s_waitcnt vmcnt(62)
; __device__ __forceinline__ float bf2f(unsigned b) { return __uint_as_float(b << 16); }
; __device__ __forceinline__ unsigned pk2(float lo, float hi) { unsigned r; asm("v_cvt_pk_bf16_f32 %0, %1, %2" : "=v"(r) : "v"(lo), "v"(hi)); return r; }
; __device__ __forceinline__ float gelu_t(float x) { return x * __builtin_amdgcn_rcpf(1.f + __expf(-1.5957691216057308f * (x + 0.044715f * x * x * x))); }
; __device__ __forceinline__ void act_item(int item, u16* UP, const u16* HALO, const float* sconv, const float* wconv, const float* bconv, float* out, int lane) {
;     ...
;         for (int t = 0; t < 16; ++t) {
;             const int row = rb * 64 + tb + t;
;             if (sample && (t & 3) == 0) { const int ns = (row - TP) >> 2; const float* s0 = sconv + (size_t)ns * 2 * FF2;
;                 const f32x2 a = *(const f32x2*)(s0 + j0), b = *(const f32x2*)(s0 + FF + j0), c = *(const f32x2*)(s0 + FF2 + j0), dd = *(const f32x2*)(s0 + FF2 + FF + j0);
;                 g2[0] = a.x; g2[1] = a.y; v2[0] = b.x; v2[1] = b.y; g1[0] = c.x; g1[1] = c.y; v1[0] = dd.x; v1[1] = dd.y; }
;             const float g0[2] = {bf2f(gw[t] & 0xffffu), bf2f(gw[t] >> 16)}, v0[2] = {bf2f(vw[t] & 0xffffu), bf2f(vw[t] >> 16)};
;             float res[2];
; #pragma unroll
;             for (int p = 0; p < 2; ++p) { const float cgv = bg[p] + wgt[0][p] * g2[p] + wgt[1][p] * g1[p] + wgt[2][p] * g0[p];
;                 const float cvv = bv[p] + wvl[0][p] * v2[p] + wvl[1][p] * v1[p] + wvl[2][p] * v0[p]; res[p] = gelu_t(cgv) * cvv;
;                 g2[p] = g1[p]; g1[p] = g0[p]; v2[p] = v1[p]; v1[p] = v0[p]; }
;             *(unsigned*)(UP + (size_t)row * FF2 + j0) = pk2(res[0], res[1]);
	v_lshlrev_b32_e32 v24, 16, v226
	v_and_b32_e32 v25, 0xffff0000, v226
	v_lshlrev_b32_e32 v26, 16, v227
	v_and_b32_e32 v27, 0xffff0000, v227
	v_lshlrev_b32_e32 v28, 16, v228
	v_and_b32_e32 v29, 0xffff0000, v228
	v_lshlrev_b32_e32 v30, 16, v229
	v_and_b32_e32 v31, 0xffff0000, v229
	v_lshlrev_b32_e32 v20, 16, v160
	v_and_b32_e32 v21, 0xffff0000, v160
	v_lshlrev_b32_e32 v22, 16, v161
	v_and_b32_e32 v23, 0xffff0000, v161
	v_pk_fma_f32 v[32:33], v[4:5], v[24:25], v[16:17]
	v_pk_fma_f32 v[34:35], v[6:7], v[26:27], v[18:19]
	v_pk_fma_f32 v[32:33], v[8:9], v[28:29], v[32:33]
	v_pk_fma_f32 v[34:35], v[10:11], v[30:31], v[34:35]
	v_pk_fma_f32 v[32:33], v[12:13], v[20:21], v[32:33]
	v_pk_fma_f32 v[34:35], v[14:15], v[22:23], v[34:35]
	v_pk_mul_f32 v[36:37], v[32:33], s[58:59]
	v_pk_mul_f32 v[36:37], v[32:33], v[36:37]
	v_pk_fma_f32 v[36:37], v[32:33], v[36:37], v[32:33]
	v_pk_mul_f32 v[36:37], v[36:37], s[60:61]
	v_pk_mul_f32 v[36:37], v[36:37], s[68:69]
	v_exp_f32_e32 v38, v36
	v_exp_f32_e32 v39, v37
	s_nop 0
	v_pk_add_f32 v[38:39], v[38:39], s[82:83]
	v_rcp_f32_e32 v38, v38
	v_rcp_f32_e32 v39, v39
	s_nop 0
	v_pk_mul_f32 v[36:37], v[32:33], v[38:39]
	v_pk_mul_f32 v[36:37], v[34:35], v[36:37]
	v_cvt_pk_bf16_f32 v224, v36, v37
	global_store_dword v2, v224, s[66:67]
	s_add_u32 s66, s66, 0x2c00
	s_addc_u32 s67, s67, 0
	s_waitcnt vmcnt(61)
	v_lshlrev_b32_e32 v24, 16, v162
	v_and_b32_e32 v25, 0xffff0000, v162
	v_lshlrev_b32_e32 v26, 16, v163
	v_and_b32_e32 v27, 0xffff0000, v163
	v_pk_fma_f32 v[32:33], v[4:5], v[28:29], v[16:17]
	v_pk_fma_f32 v[34:35], v[6:7], v[30:31], v[18:19]
	v_pk_fma_f32 v[32:33], v[8:9], v[20:21], v[32:33]
	v_pk_fma_f32 v[34:35], v[10:11], v[22:23], v[34:35]
	v_pk_fma_f32 v[32:33], v[12:13], v[24:25], v[32:33]
	v_pk_fma_f32 v[34:35], v[14:15], v[26:27], v[34:35]
	v_pk_mul_f32 v[36:37], v[32:33], s[58:59]
	v_pk_mul_f32 v[36:37], v[32:33], v[36:37]
	v_pk_fma_f32 v[36:37], v[32:33], v[36:37], v[32:33]
	v_pk_mul_f32 v[36:37], v[36:37], s[60:61]
	v_pk_mul_f32 v[36:37], v[36:37], s[68:69]
	v_exp_f32_e32 v38, v36
	v_exp_f32_e32 v39, v37
	s_nop 0
	v_pk_add_f32 v[38:39], v[38:39], s[82:83]
	v_rcp_f32_e32 v38, v38
	v_rcp_f32_e32 v39, v39
	s_nop 0
	v_pk_mul_f32 v[36:37], v[32:33], v[38:39]
	v_pk_mul_f32 v[36:37], v[34:35], v[36:37]
	v_cvt_pk_bf16_f32 v224, v36, v37
	global_store_dword v2, v224, s[66:67]
	s_add_u32 s66, s66, 0x2c00
	s_addc_u32 s67, s67, 0
	s_waitcnt vmcnt(60)
	v_lshlrev_b32_e32 v28, 16, v164
	v_and_b32_e32 v29, 0xffff0000, v164
	v_lshlrev_b32_e32 v30, 16, v165
	v_and_b32_e32 v31, 0xffff0000, v165
	v_pk_fma_f32 v[32:33], v[4:5], v[20:21], v[16:17]
	v_pk_fma_f32 v[34:35], v[6:7], v[22:23], v[18:19]
	v_pk_fma_f32 v[32:33], v[8:9], v[24:25], v[32:33]
	v_pk_fma_f32 v[34:35], v[10:11], v[26:27], v[34:35]
	v_pk_fma_f32 v[32:33], v[12:13], v[28:29], v[32:33]
	v_pk_fma_f32 v[34:35], v[14:15], v[30:31], v[34:35]
	v_pk_mul_f32 v[36:37], v[32:33], s[58:59]
	v_pk_mul_f32 v[36:37], v[32:33], v[36:37]
	v_pk_fma_f32 v[36:37], v[32:33], v[36:37], v[32:33]
	v_pk_mul_f32 v[36:37], v[36:37], s[60:61]
	v_pk_mul_f32 v[36:37], v[36:37], s[68:69]
	v_exp_f32_e32 v38, v36
	v_exp_f32_e32 v39, v37
	s_nop 0
	v_pk_add_f32 v[38:39], v[38:39], s[82:83]
	v_rcp_f32_e32 v38, v38
	v_rcp_f32_e32 v39, v39
	s_nop 0
	v_pk_mul_f32 v[36:37], v[32:33], v[38:39]
	v_pk_mul_f32 v[36:37], v[34:35], v[36:37]
	v_cvt_pk_bf16_f32 v224, v36, v37
	global_store_dword v2, v224, s[66:67]
	s_add_u32 s66, s66, 0x2c00
	s_addc_u32 s67, s67, 0
	s_waitcnt vmcnt(59)
	v_lshlrev_b32_e32 v20, 16, v166
	v_and_b32_e32 v21, 0xffff0000, v166
	v_lshlrev_b32_e32 v22, 16, v167
	v_and_b32_e32 v23, 0xffff0000, v167
	v_pk_fma_f32 v[32:33], v[4:5], v[24:25], v[16:17]
	v_pk_fma_f32 v[34:35], v[6:7], v[26:27], v[18:19]
	v_pk_fma_f32 v[32:33], v[8:9], v[28:29], v[32:33]
	v_pk_fma_f32 v[34:35], v[10:11], v[30:31], v[34:35]
	v_pk_fma_f32 v[32:33], v[12:13], v[20:21], v[32:33]
	v_pk_fma_f32 v[34:35], v[14:15], v[22:23], v[34:35]
	v_pk_mul_f32 v[36:37], v[32:33], s[58:59]
	v_pk_mul_f32 v[36:37], v[32:33], v[36:37]
	v_pk_fma_f32 v[36:37], v[32:33], v[36:37], v[32:33]
	v_pk_mul_f32 v[36:37], v[36:37], s[60:61]
	v_pk_mul_f32 v[36:37], v[36:37], s[68:69]
	v_exp_f32_e32 v38, v36
	v_exp_f32_e32 v39, v37
	s_nop 0
	v_pk_add_f32 v[38:39], v[38:39], s[82:83]
	v_rcp_f32_e32 v38, v38
	v_rcp_f32_e32 v39, v39
	s_nop 0
	v_pk_mul_f32 v[36:37], v[32:33], v[38:39]
	v_pk_mul_f32 v[36:37], v[34:35], v[36:37]
	v_cvt_pk_bf16_f32 v224, v36, v37
	global_store_dword v2, v224, s[66:67]
	s_add_u32 s66, s66, 0x2c00
	s_addc_u32 s67, s67, 0
	s_waitcnt vmcnt(58)
	v_lshlrev_b32_e32 v24, 16, v168
	v_and_b32_e32 v25, 0xffff0000, v168
	v_lshlrev_b32_e32 v26, 16, v169
	v_and_b32_e32 v27, 0xffff0000, v169
	v_pk_fma_f32 v[32:33], v[4:5], v[28:29], v[16:17]
	v_pk_fma_f32 v[34:35], v[6:7], v[30:31], v[18:19]
	v_pk_fma_f32 v[32:33], v[8:9], v[20:21], v[32:33]
	v_pk_fma_f32 v[34:35], v[10:11], v[22:23], v[34:35]
	v_pk_fma_f32 v[32:33], v[12:13], v[24:25], v[32:33]
	v_pk_fma_f32 v[34:35], v[14:15], v[26:27], v[34:35]
	v_pk_mul_f32 v[36:37], v[32:33], s[58:59]
	v_pk_mul_f32 v[36:37], v[32:33], v[36:37]
	v_pk_fma_f32 v[36:37], v[32:33], v[36:37], v[32:33]
	v_pk_mul_f32 v[36:37], v[36:37], s[60:61]
	v_pk_mul_f32 v[36:37], v[36:37], s[68:69]
	v_exp_f32_e32 v38, v36
	v_exp_f32_e32 v39, v37
	s_nop 0
	v_pk_add_f32 v[38:39], v[38:39], s[82:83]
	v_rcp_f32_e32 v38, v38
	v_rcp_f32_e32 v39, v39
	s_nop 0
	v_pk_mul_f32 v[36:37], v[32:33], v[38:39]
	v_pk_mul_f32 v[36:37], v[34:35], v[36:37]
	v_cvt_pk_bf16_f32 v224, v36, v37
	global_store_dword v2, v224, s[66:67]
	s_add_u32 s66, s66, 0x2c00
	s_addc_u32 s67, s67, 0
	s_waitcnt vmcnt(57)
; __device__ __forceinline__ float bf2f(unsigned b) { return __uint_as_float(b << 16); }
; __device__ __forceinline__ unsigned pk2(float lo, float hi) { unsigned r; asm("v_cvt_pk_bf16_f32 %0, %1, %2" : "=v"(r) : "v"(lo), "v"(hi)); return r; }
; __device__ __forceinline__ float gelu_t(float x) { return x * __builtin_amdgcn_rcpf(1.f + __expf(-1.5957691216057308f * (x + 0.044715f * x * x * x))); }
; __device__ __forceinline__ void act_item(int item, u16* UP, const u16* HALO, const float* sconv, const float* wconv, const float* bconv, float* out, int lane) {
;     ...
;         for (int t = 0; t < 16; ++t) {
;             const int row = rb * 64 + tb + t;
;             if (sample && (t & 3) == 0) { const int ns = (row - TP) >> 2; const float* s0 = sconv + (size_t)ns * 2 * FF2;
;                 const f32x2 a = *(const f32x2*)(s0 + j0), b = *(const f32x2*)(s0 + FF + j0), c = *(const f32x2*)(s0 + FF2 + j0), dd = *(const f32x2*)(s0 + FF2 + FF + j0);
;                 g2[0] = a.x; g2[1] = a.y; v2[0] = b.x; v2[1] = b.y; g1[0] = c.x; g1[1] = c.y; v1[0] = dd.x; v1[1] = dd.y; }
;             const float g0[2] = {bf2f(gw[t] & 0xffffu), bf2f(gw[t] >> 16)}, v0[2] = {bf2f(vw[t] & 0xffffu), bf2f(vw[t] >> 16)};
;             float res[2];
; #pragma unroll
;             for (int p = 0; p < 2; ++p) { const float cgv = bg[p] + wgt[0][p] * g2[p] + wgt[1][p] * g1[p] + wgt[2][p] * g0[p];
;                 const float cvv = bv[p] + wvl[0][p] * v2[p] + wvl[1][p] * v1[p] + wvl[2][p] * v0[p]; res[p] = gelu_t(cgv) * cvv;
;                 g2[p] = g1[p]; g1[p] = g0[p]; v2[p] = v1[p]; v1[p] = v0[p]; }
;             *(unsigned*)(UP + (size_t)row * FF2 + j0) = pk2(res[0], res[1]);
	v_lshlrev_b32_e32 v28, 16, v170
	v_and_b32_e32 v29, 0xffff0000, v170
	v_lshlrev_b32_e32 v30, 16, v171
	v_and_b32_e32 v31, 0xffff0000, v171
	v_pk_fma_f32 v[32:33], v[4:5], v[20:21], v[16:17]
	v_pk_fma_f32 v[34:35], v[6:7], v[22:23], v[18:19]
	v_pk_fma_f32 v[32:33], v[8:9], v[24:25], v[32:33]
	v_pk_fma_f32 v[34:35], v[10:11], v[26:27], v[34:35]
	v_pk_fma_f32 v[32:33], v[12:13], v[28:29], v[32:33]
	v_pk_fma_f32 v[34:35], v[14:15], v[30:31], v[34:35]
	v_pk_mul_f32 v[36:37], v[32:33], s[58:59]
	v_pk_mul_f32 v[36:37], v[32:33], v[36:37]
	v_pk_fma_f32 v[36:37], v[32:33], v[36:37], v[32:33]
	v_pk_mul_f32 v[36:37], v[36:37], s[60:61]
	v_pk_mul_f32 v[36:37], v[36:37], s[68:69]
	v_exp_f32_e32 v38, v36
	v_exp_f32_e32 v39, v37
	s_nop 0
	v_pk_add_f32 v[38:39], v[38:39], s[82:83]
	v_rcp_f32_e32 v38, v38
	v_rcp_f32_e32 v39, v39
	s_nop 0
	v_pk_mul_f32 v[36:37], v[32:33], v[38:39]
	v_pk_mul_f32 v[36:37], v[34:35], v[36:37]
	v_cvt_pk_bf16_f32 v224, v36, v37
	global_store_dword v2, v224, s[66:67]
	s_add_u32 s66, s66, 0x2c00
	s_addc_u32 s67, s67, 0
	s_waitcnt vmcnt(56)
	v_lshlrev_b32_e32 v20, 16, v172
	v_and_b32_e32 v21, 0xffff0000, v172
	v_lshlrev_b32_e32 v22, 16, v173
	v_and_b32_e32 v23, 0xffff0000, v173
	v_pk_fma_f32 v[32:33], v[4:5], v[24:25], v[16:17]
	v_pk_fma_f32 v[34:35], v[6:7], v[26:27], v[18:19]
	v_pk_fma_f32 v[32:33], v[8:9], v[28:29], v[32:33]
	v_pk_fma_f32 v[34:35], v[10:11], v[30:31], v[34:35]
	v_pk_fma_f32 v[32:33], v[12:13], v[20:21], v[32:33]
	v_pk_fma_f32 v[34:35], v[14:15], v[22:23], v[34:35]
	v_pk_mul_f32 v[36:37], v[32:33], s[58:59]
	v_pk_mul_f32 v[36:37], v[32:33], v[36:37]
	v_pk_fma_f32 v[36:37], v[32:33], v[36:37], v[32:33]
	v_pk_mul_f32 v[36:37], v[36:37], s[60:61]
	v_pk_mul_f32 v[36:37], v[36:37], s[68:69]
	v_exp_f32_e32 v38, v36
	v_exp_f32_e32 v39, v37
	s_nop 0
	v_pk_add_f32 v[38:39], v[38:39], s[82:83]
	v_rcp_f32_e32 v38, v38
	v_rcp_f32_e32 v39, v39
	s_nop 0
	v_pk_mul_f32 v[36:37], v[32:33], v[38:39]
	v_pk_mul_f32 v[36:37], v[34:35], v[36:37]
	v_cvt_pk_bf16_f32 v224, v36, v37
	global_store_dword v2, v224, s[66:67]
	s_add_u32 s66, s66, 0x2c00
	s_addc_u32 s67, s67, 0
	s_waitcnt vmcnt(55)
	v_lshlrev_b32_e32 v24, 16, v174
	v_and_b32_e32 v25, 0xffff0000, v174
	v_lshlrev_b32_e32 v26, 16, v175
	v_and_b32_e32 v27, 0xffff0000, v175
	v_pk_fma_f32 v[32:33], v[4:5], v[28:29], v[16:17]
	v_pk_fma_f32 v[34:35], v[6:7], v[30:31], v[18:19]
	v_pk_fma_f32 v[32:33], v[8:9], v[20:21], v[32:33]
	v_pk_fma_f32 v[34:35], v[10:11], v[22:23], v[34:35]
	v_pk_fma_f32 v[32:33], v[12:13], v[24:25], v[32:33]
	v_pk_fma_f32 v[34:35], v[14:15], v[26:27], v[34:35]
	v_pk_mul_f32 v[36:37], v[32:33], s[58:59]
	v_pk_mul_f32 v[36:37], v[32:33], v[36:37]
	v_pk_fma_f32 v[36:37], v[32:33], v[36:37], v[32:33]
	v_pk_mul_f32 v[36:37], v[36:37], s[60:61]
	v_pk_mul_f32 v[36:37], v[36:37], s[68:69]
	v_exp_f32_e32 v38, v36
	v_exp_f32_e32 v39, v37
	s_nop 0
	v_pk_add_f32 v[38:39], v[38:39], s[82:83]
	v_rcp_f32_e32 v38, v38
	v_rcp_f32_e32 v39, v39
	s_nop 0
	v_pk_mul_f32 v[36:37], v[32:33], v[38:39]
	v_pk_mul_f32 v[36:37], v[34:35], v[36:37]
	v_cvt_pk_bf16_f32 v224, v36, v37
	global_store_dword v2, v224, s[66:67]
	s_add_u32 s66, s66, 0x2c00
	s_addc_u32 s67, s67, 0
	s_waitcnt vmcnt(54)
	v_lshlrev_b32_e32 v28, 16, v176
	v_and_b32_e32 v29, 0xffff0000, v176
	v_lshlrev_b32_e32 v30, 16, v177
	v_and_b32_e32 v31, 0xffff0000, v177
	v_pk_fma_f32 v[32:33], v[4:5], v[20:21], v[16:17]
	v_pk_fma_f32 v[34:35], v[6:7], v[22:23], v[18:19]
	v_pk_fma_f32 v[32:33], v[8:9], v[24:25], v[32:33]
	v_pk_fma_f32 v[34:35], v[10:11], v[26:27], v[34:35]
	v_pk_fma_f32 v[32:33], v[12:13], v[28:29], v[32:33]
	v_pk_fma_f32 v[34:35], v[14:15], v[30:31], v[34:35]
	v_pk_mul_f32 v[36:37], v[32:33], s[58:59]
	v_pk_mul_f32 v[36:37], v[32:33], v[36:37]
	v_pk_fma_f32 v[36:37], v[32:33], v[36:37], v[32:33]
	v_pk_mul_f32 v[36:37], v[36:37], s[60:61]
	v_pk_mul_f32 v[36:37], v[36:37], s[68:69]
	v_exp_f32_e32 v38, v36
	v_exp_f32_e32 v39, v37
	s_nop 0
	v_pk_add_f32 v[38:39], v[38:39], s[82:83]
	v_rcp_f32_e32 v38, v38
	v_rcp_f32_e32 v39, v39
	s_nop 0
	v_pk_mul_f32 v[36:37], v[32:33], v[38:39]
	v_pk_mul_f32 v[36:37], v[34:35], v[36:37]
	v_cvt_pk_bf16_f32 v224, v36, v37
	global_store_dword v2, v224, s[66:67]
	s_add_u32 s66, s66, 0x2c00
	s_addc_u32 s67, s67, 0
	s_waitcnt vmcnt(53)
	v_lshlrev_b32_e32 v20, 16, v178
	v_and_b32_e32 v21, 0xffff0000, v178
	v_lshlrev_b32_e32 v22, 16, v179
	v_and_b32_e32 v23, 0xffff0000, v179
	v_pk_fma_f32 v[32:33], v[4:5], v[24:25], v[16:17]
	v_pk_fma_f32 v[34:35], v[6:7], v[26:27], v[18:19]
	v_pk_fma_f32 v[32:33], v[8:9], v[28:29], v[32:33]
	v_pk_fma_f32 v[34:35], v[10:11], v[30:31], v[34:35]
	v_pk_fma_f32 v[32:33], v[12:13], v[20:21], v[32:33]
	v_pk_fma_f32 v[34:35], v[14:15], v[22:23], v[34:35]
	v_pk_mul_f32 v[36:37], v[32:33], s[58:59]
	v_pk_mul_f32 v[36:37], v[32:33], v[36:37]
	v_pk_fma_f32 v[36:37], v[32:33], v[36:37], v[32:33]
	v_pk_mul_f32 v[36:37], v[36:37], s[60:61]
	v_pk_mul_f32 v[36:37], v[36:37], s[68:69]
	v_exp_f32_e32 v38, v36
	v_exp_f32_e32 v39, v37
	s_nop 0
	v_pk_add_f32 v[38:39], v[38:39], s[82:83]
	v_rcp_f32_e32 v38, v38
	v_rcp_f32_e32 v39, v39
	s_nop 0
	v_pk_mul_f32 v[36:37], v[32:33], v[38:39]
	v_pk_mul_f32 v[36:37], v[34:35], v[36:37]
	v_cvt_pk_bf16_f32 v224, v36, v37
	global_store_dword v2, v224, s[66:67]
	s_add_u32 s66, s66, 0x2c00
	s_addc_u32 s67, s67, 0
	s_waitcnt vmcnt(52)
; __device__ __forceinline__ float bf2f(unsigned b) { return __uint_as_float(b << 16); }
; __device__ __forceinline__ unsigned pk2(float lo, float hi) { unsigned r; asm("v_cvt_pk_bf16_f32 %0, %1, %2" : "=v"(r) : "v"(lo), "v"(hi)); return r; }
; __device__ __forceinline__ float gelu_t(float x) { return x * __builtin_amdgcn_rcpf(1.f + __expf(-1.5957691216057308f * (x + 0.044715f * x * x * x))); }
; __device__ __forceinline__ void act_item(int item, u16* UP, const u16* HALO, const float* sconv, const float* wconv, const float* bconv, float* out, int lane) {
;     ...
;         for (int t = 0; t < 16; ++t) {
;             const int row = rb * 64 + tb + t;
;             if (sample && (t & 3) == 0) { const int ns = (row - TP) >> 2; const float* s0 = sconv + (size_t)ns * 2 * FF2;
;                 const f32x2 a = *(const f32x2*)(s0 + j0), b = *(const f32x2*)(s0 + FF + j0), c = *(const f32x2*)(s0 + FF2 + j0), dd = *(const f32x2*)(s0 + FF2 + FF + j0);
;                 g2[0] = a.x; g2[1] = a.y; v2[0] = b.x; v2[1] = b.y; g1[0] = c.x; g1[1] = c.y; v1[0] = dd.x; v1[1] = dd.y; }
;             const float g0[2] = {bf2f(gw[t] & 0xffffu), bf2f(gw[t] >> 16)}, v0[2] = {bf2f(vw[t] & 0xffffu), bf2f(vw[t] >> 16)};
;             float res[2];
; #pragma unroll
;             for (int p = 0; p < 2; ++p) { const float cgv = bg[p] + wgt[0][p] * g2[p] + wgt[1][p] * g1[p] + wgt[2][p] * g0[p];
;                 const float cvv = bv[p] + wvl[0][p] * v2[p] + wvl[1][p] * v1[p] + wvl[2][p] * v0[p]; res[p] = gelu_t(cgv) * cvv;
;                 g2[p] = g1[p]; g1[p] = g0[p]; v2[p] = v1[p]; v1[p] = v0[p]; }
;             *(unsigned*)(UP + (size_t)row * FF2 + j0) = pk2(res[0], res[1]);
	v_lshlrev_b32_e32 v24, 16, v180
	v_and_b32_e32 v25, 0xffff0000, v180
	v_lshlrev_b32_e32 v26, 16, v181
	v_and_b32_e32 v27, 0xffff0000, v181
	v_pk_fma_f32 v[32:33], v[4:5], v[28:29], v[16:17]
	v_pk_fma_f32 v[34:35], v[6:7], v[30:31], v[18:19]
	v_pk_fma_f32 v[32:33], v[8:9], v[20:21], v[32:33]
	v_pk_fma_f32 v[34:35], v[10:11], v[22:23], v[34:35]
	v_pk_fma_f32 v[32:33], v[12:13], v[24:25], v[32:33]
	v_pk_fma_f32 v[34:35], v[14:15], v[26:27], v[34:35]
	v_pk_mul_f32 v[36:37], v[32:33], s[58:59]
	v_pk_mul_f32 v[36:37], v[32:33], v[36:37]
	v_pk_fma_f32 v[36:37], v[32:33], v[36:37], v[32:33]
	v_pk_mul_f32 v[36:37], v[36:37], s[60:61]
	v_pk_mul_f32 v[36:37], v[36:37], s[68:69]
	v_exp_f32_e32 v38, v36
	v_exp_f32_e32 v39, v37
	s_nop 0
	v_pk_add_f32 v[38:39], v[38:39], s[82:83]
	v_rcp_f32_e32 v38, v38
	v_rcp_f32_e32 v39, v39
	s_nop 0
	v_pk_mul_f32 v[36:37], v[32:33], v[38:39]
	v_pk_mul_f32 v[36:37], v[34:35], v[36:37]
	v_cvt_pk_bf16_f32 v224, v36, v37
	global_store_dword v2, v224, s[66:67]
	s_add_u32 s66, s66, 0x2c00
	s_addc_u32 s67, s67, 0
	s_waitcnt vmcnt(51)
	v_lshlrev_b32_e32 v28, 16, v182
	v_and_b32_e32 v29, 0xffff0000, v182
	v_lshlrev_b32_e32 v30, 16, v183
	v_and_b32_e32 v31, 0xffff0000, v183
	v_pk_fma_f32 v[32:33], v[4:5], v[20:21], v[16:17]
	v_pk_fma_f32 v[34:35], v[6:7], v[22:23], v[18:19]
	v_pk_fma_f32 v[32:33], v[8:9], v[24:25], v[32:33]
	v_pk_fma_f32 v[34:35], v[10:11], v[26:27], v[34:35]
	v_pk_fma_f32 v[32:33], v[12:13], v[28:29], v[32:33]
	v_pk_fma_f32 v[34:35], v[14:15], v[30:31], v[34:35]
	v_pk_mul_f32 v[36:37], v[32:33], s[58:59]
	v_pk_mul_f32 v[36:37], v[32:33], v[36:37]
	v_pk_fma_f32 v[36:37], v[32:33], v[36:37], v[32:33]
	v_pk_mul_f32 v[36:37], v[36:37], s[60:61]
	v_pk_mul_f32 v[36:37], v[36:37], s[68:69]
	v_exp_f32_e32 v38, v36
	v_exp_f32_e32 v39, v37
	s_nop 0
	v_pk_add_f32 v[38:39], v[38:39], s[82:83]
	v_rcp_f32_e32 v38, v38
	v_rcp_f32_e32 v39, v39
	s_nop 0
	v_pk_mul_f32 v[36:37], v[32:33], v[38:39]
	v_pk_mul_f32 v[36:37], v[34:35], v[36:37]
	v_cvt_pk_bf16_f32 v224, v36, v37
	global_store_dword v2, v224, s[66:67]
	s_add_u32 s66, s66, 0x2c00
	s_addc_u32 s67, s67, 0
	s_waitcnt vmcnt(50)
	v_lshlrev_b32_e32 v20, 16, v184
	v_and_b32_e32 v21, 0xffff0000, v184
	v_lshlrev_b32_e32 v22, 16, v185
	v_and_b32_e32 v23, 0xffff0000, v185
	v_pk_fma_f32 v[32:33], v[4:5], v[24:25], v[16:17]
	v_pk_fma_f32 v[34:35], v[6:7], v[26:27], v[18:19]
	v_pk_fma_f32 v[32:33], v[8:9], v[28:29], v[32:33]
	v_pk_fma_f32 v[34:35], v[10:11], v[30:31], v[34:35]
	v_pk_fma_f32 v[32:33], v[12:13], v[20:21], v[32:33]
	v_pk_fma_f32 v[34:35], v[14:15], v[22:23], v[34:35]
	v_pk_mul_f32 v[36:37], v[32:33], s[58:59]
	v_pk_mul_f32 v[36:37], v[32:33], v[36:37]
	v_pk_fma_f32 v[36:37], v[32:33], v[36:37], v[32:33]
	v_pk_mul_f32 v[36:37], v[36:37], s[60:61]
	v_pk_mul_f32 v[36:37], v[36:37], s[68:69]
	v_exp_f32_e32 v38, v36
	v_exp_f32_e32 v39, v37
	s_nop 0
	v_pk_add_f32 v[38:39], v[38:39], s[82:83]
	v_rcp_f32_e32 v38, v38
	v_rcp_f32_e32 v39, v39
	s_nop 0
	v_pk_mul_f32 v[36:37], v[32:33], v[38:39]
	v_pk_mul_f32 v[36:37], v[34:35], v[36:37]
	v_cvt_pk_bf16_f32 v224, v36, v37
	global_store_dword v2, v224, s[66:67]
	s_add_u32 s66, s66, 0x2c00
	s_addc_u32 s67, s67, 0
	s_waitcnt vmcnt(49)
	v_lshlrev_b32_e32 v24, 16, v186
	v_and_b32_e32 v25, 0xffff0000, v186
	v_lshlrev_b32_e32 v26, 16, v187
	v_and_b32_e32 v27, 0xffff0000, v187
	v_pk_fma_f32 v[32:33], v[4:5], v[28:29], v[16:17]
	v_pk_fma_f32 v[34:35], v[6:7], v[30:31], v[18:19]
	v_pk_fma_f32 v[32:33], v[8:9], v[20:21], v[32:33]
	v_pk_fma_f32 v[34:35], v[10:11], v[22:23], v[34:35]
	v_pk_fma_f32 v[32:33], v[12:13], v[24:25], v[32:33]
	v_pk_fma_f32 v[34:35], v[14:15], v[26:27], v[34:35]
	v_pk_mul_f32 v[36:37], v[32:33], s[58:59]
	v_pk_mul_f32 v[36:37], v[32:33], v[36:37]
	v_pk_fma_f32 v[36:37], v[32:33], v[36:37], v[32:33]
	v_pk_mul_f32 v[36:37], v[36:37], s[60:61]
	v_pk_mul_f32 v[36:37], v[36:37], s[68:69]
	v_exp_f32_e32 v38, v36
	v_exp_f32_e32 v39, v37
	s_nop 0
	v_pk_add_f32 v[38:39], v[38:39], s[82:83]
	v_rcp_f32_e32 v38, v38
	v_rcp_f32_e32 v39, v39
	s_nop 0
	v_pk_mul_f32 v[36:37], v[32:33], v[38:39]
	v_pk_mul_f32 v[36:37], v[34:35], v[36:37]
	v_cvt_pk_bf16_f32 v224, v36, v37
	global_store_dword v2, v224, s[66:67]
	s_add_u32 s66, s66, 0x2c00
	s_addc_u32 s67, s67, 0
	s_waitcnt vmcnt(48)
	v_lshlrev_b32_e32 v28, 16, v188
	v_and_b32_e32 v29, 0xffff0000, v188
	v_lshlrev_b32_e32 v30, 16, v189
	v_and_b32_e32 v31, 0xffff0000, v189
	v_pk_fma_f32 v[32:33], v[4:5], v[20:21], v[16:17]
	v_pk_fma_f32 v[34:35], v[6:7], v[22:23], v[18:19]
	v_pk_fma_f32 v[32:33], v[8:9], v[24:25], v[32:33]
	v_pk_fma_f32 v[34:35], v[10:11], v[26:27], v[34:35]
	v_pk_fma_f32 v[32:33], v[12:13], v[28:29], v[32:33]
	v_pk_fma_f32 v[34:35], v[14:15], v[30:31], v[34:35]
	v_pk_mul_f32 v[36:37], v[32:33], s[58:59]
	v_pk_mul_f32 v[36:37], v[32:33], v[36:37]
	v_pk_fma_f32 v[36:37], v[32:33], v[36:37], v[32:33]
	v_pk_mul_f32 v[36:37], v[36:37], s[60:61]
	v_pk_mul_f32 v[36:37], v[36:37], s[68:69]
	v_exp_f32_e32 v38, v36
	v_exp_f32_e32 v39, v37
	s_nop 0
	v_pk_add_f32 v[38:39], v[38:39], s[82:83]
	v_rcp_f32_e32 v38, v38
	v_rcp_f32_e32 v39, v39
	s_nop 0
	v_pk_mul_f32 v[36:37], v[32:33], v[38:39]
	v_pk_mul_f32 v[36:37], v[34:35], v[36:37]
	v_cvt_pk_bf16_f32 v224, v36, v37
	global_store_dword v2, v224, s[66:67]
	s_add_u32 s66, s66, 0x2c00
	s_addc_u32 s67, s67, 0
	s_waitcnt vmcnt(47)
; __device__ __forceinline__ float bf2f(unsigned b) { return __uint_as_float(b << 16); }
; __device__ __forceinline__ unsigned pk2(float lo, float hi) { unsigned r; asm("v_cvt_pk_bf16_f32 %0, %1, %2" : "=v"(r) : "v"(lo), "v"(hi)); return r; }
; __device__ __forceinline__ float gelu_t(float x) { return x * __builtin_amdgcn_rcpf(1.f + __expf(-1.5957691216057308f * (x + 0.044715f * x * x * x))); }
; __device__ __forceinline__ void act_item(int item, u16* UP, const u16* HALO, const float* sconv, const float* wconv, const float* bconv, float* out, int lane) {
;     ...
;         for (int t = 0; t < 16; ++t) { const size_t row = (size_t)rb * 64 + tb + t; gw[t] = *(const unsigned*)(UP + row * FF2 + j0); vw[t] = *(const unsigned*)(UP + row * FF2 + FF + j0); }
; #pragma unroll
;         for (int t = 0; t < 16; ++t) {
;             const int row = rb * 64 + tb + t;
;             if (sample && (t & 3) == 0) { const int ns = (row - TP) >> 2; const float* s0 = sconv + (size_t)ns * 2 * FF2;
;                 const f32x2 a = *(const f32x2*)(s0 + j0), b = *(const f32x2*)(s0 + FF + j0), c = *(const f32x2*)(s0 + FF2 + j0), dd = *(const f32x2*)(s0 + FF2 + FF + j0);
;                 g2[0] = a.x; g2[1] = a.y; v2[0] = b.x; v2[1] = b.y; g1[0] = c.x; g1[1] = c.y; v1[0] = dd.x; v1[1] = dd.y; }
;             const float g0[2] = {bf2f(gw[t] & 0xffffu), bf2f(gw[t] >> 16)}, v0[2] = {bf2f(vw[t] & 0xffffu), bf2f(vw[t] >> 16)};
;             float res[2];
; #pragma unroll
;             for (int p = 0; p < 2; ++p) { const float cgv = bg[p] + wgt[0][p] * g2[p] + wgt[1][p] * g1[p] + wgt[2][p] * g0[p];
;                 const float cvv = bv[p] + wvl[0][p] * v2[p] + wvl[1][p] * v1[p] + wvl[2][p] * v0[p]; res[p] = gelu_t(cgv) * cvv;
;                 g2[p] = g1[p]; g1[p] = g0[p]; v2[p] = v1[p]; v1[p] = v0[p]; }
;             *(unsigned*)(UP + (size_t)row * FF2 + j0) = pk2(res[0], res[1]);
	v_lshlrev_b32_e32 v20, 16, v190
	v_and_b32_e32 v21, 0xffff0000, v190
	v_lshlrev_b32_e32 v22, 16, v191
	v_and_b32_e32 v23, 0xffff0000, v191
	v_pk_fma_f32 v[32:33], v[4:5], v[24:25], v[16:17]
	v_pk_fma_f32 v[34:35], v[6:7], v[26:27], v[18:19]
	v_pk_fma_f32 v[32:33], v[8:9], v[28:29], v[32:33]
	v_pk_fma_f32 v[34:35], v[10:11], v[30:31], v[34:35]
	v_pk_fma_f32 v[32:33], v[12:13], v[20:21], v[32:33]
	v_pk_fma_f32 v[34:35], v[14:15], v[22:23], v[34:35]
	v_pk_mul_f32 v[36:37], v[32:33], s[58:59]
	v_pk_mul_f32 v[36:37], v[32:33], v[36:37]
	v_pk_fma_f32 v[36:37], v[32:33], v[36:37], v[32:33]
	v_pk_mul_f32 v[36:37], v[36:37], s[60:61]
	v_pk_mul_f32 v[36:37], v[36:37], s[68:69]
	v_exp_f32_e32 v38, v36
	v_exp_f32_e32 v39, v37
	s_nop 0
	v_pk_add_f32 v[38:39], v[38:39], s[82:83]
	v_rcp_f32_e32 v38, v38
	v_rcp_f32_e32 v39, v39
	s_nop 0
	v_pk_mul_f32 v[36:37], v[32:33], v[38:39]
	v_pk_mul_f32 v[36:37], v[34:35], v[36:37]
	v_cvt_pk_bf16_f32 v224, v36, v37
	global_store_dword v2, v224, s[66:67]
	s_add_u32 s66, s66, 0x2c00
	s_addc_u32 s67, s67, 0
	global_load_dword v160, v2, s[64:65]
	global_load_dword v161, v3, s[64:65]
	s_add_u32 s64, s64, 0x2c00
	s_addc_u32 s65, s65, 0
	global_load_dword v162, v2, s[64:65]
	global_load_dword v163, v3, s[64:65]
	s_add_u32 s64, s64, 0x2c00
	s_addc_u32 s65, s65, 0
	global_load_dword v164, v2, s[64:65]
	global_load_dword v165, v3, s[64:65]
	s_add_u32 s64, s64, 0x2c00
	s_addc_u32 s65, s65, 0
	global_load_dword v166, v2, s[64:65]
	global_load_dword v167, v3, s[64:65]
	s_add_u32 s64, s64, 0x2c00
	s_addc_u32 s65, s65, 0
	global_load_dword v168, v2, s[64:65]
	global_load_dword v169, v3, s[64:65]
	s_add_u32 s64, s64, 0x2c00
	s_addc_u32 s65, s65, 0
	global_load_dword v170, v2, s[64:65]
	global_load_dword v171, v3, s[64:65]
	s_add_u32 s64, s64, 0x2c00
	s_addc_u32 s65, s65, 0
	global_load_dword v172, v2, s[64:65]
	global_load_dword v173, v3, s[64:65]
	s_add_u32 s64, s64, 0x2c00
	s_addc_u32 s65, s65, 0
	global_load_dword v174, v2, s[64:65]
	global_load_dword v175, v3, s[64:65]
	s_add_u32 s64, s64, 0x2c00
	s_addc_u32 s65, s65, 0
	global_load_dword v176, v2, s[64:65]
	global_load_dword v177, v3, s[64:65]
	s_add_u32 s64, s64, 0x2c00
	s_addc_u32 s65, s65, 0
	global_load_dword v178, v2, s[64:65]
	global_load_dword v179, v3, s[64:65]
	s_add_u32 s64, s64, 0x2c00
	s_addc_u32 s65, s65, 0
	global_load_dword v180, v2, s[64:65]
	global_load_dword v181, v3, s[64:65]
	s_add_u32 s64, s64, 0x2c00
	s_addc_u32 s65, s65, 0
	global_load_dword v182, v2, s[64:65]
	global_load_dword v183, v3, s[64:65]
	s_add_u32 s64, s64, 0x2c00
	s_addc_u32 s65, s65, 0
	global_load_dword v184, v2, s[64:65]
	global_load_dword v185, v3, s[64:65]
	s_add_u32 s64, s64, 0x2c00
	s_addc_u32 s65, s65, 0
	global_load_dword v186, v2, s[64:65]
	global_load_dword v187, v3, s[64:65]
	s_add_u32 s64, s64, 0x2c00
	s_addc_u32 s65, s65, 0
	global_load_dword v188, v2, s[64:65]
	global_load_dword v189, v3, s[64:65]
	s_add_u32 s64, s64, 0x2c00
	s_addc_u32 s65, s65, 0
	global_load_dword v190, v2, s[64:65]
	global_load_dword v191, v3, s[64:65]
	s_add_u32 s64, s64, 0x2c00
	s_addc_u32 s65, s65, 0
	s_waitcnt vmcnt(62)
	v_lshlrev_b32_e32 v24, 16, v192
	v_and_b32_e32 v25, 0xffff0000, v192
	v_lshlrev_b32_e32 v26, 16, v193
	v_and_b32_e32 v27, 0xffff0000, v193
	v_pk_fma_f32 v[32:33], v[4:5], v[28:29], v[16:17]
	v_pk_fma_f32 v[34:35], v[6:7], v[30:31], v[18:19]
	v_pk_fma_f32 v[32:33], v[8:9], v[20:21], v[32:33]
	v_pk_fma_f32 v[34:35], v[10:11], v[22:23], v[34:35]
	v_pk_fma_f32 v[32:33], v[12:13], v[24:25], v[32:33]
	v_pk_fma_f32 v[34:35], v[14:15], v[26:27], v[34:35]
	v_pk_mul_f32 v[36:37], v[32:33], s[58:59]
	v_pk_mul_f32 v[36:37], v[32:33], v[36:37]
	v_pk_fma_f32 v[36:37], v[32:33], v[36:37], v[32:33]
	v_pk_mul_f32 v[36:37], v[36:37], s[60:61]
	v_pk_mul_f32 v[36:37], v[36:37], s[68:69]
	v_exp_f32_e32 v38, v36
	v_exp_f32_e32 v39, v37
	s_nop 0
	v_pk_add_f32 v[38:39], v[38:39], s[82:83]
	v_rcp_f32_e32 v38, v38
	v_rcp_f32_e32 v39, v39
	s_nop 0
	v_pk_mul_f32 v[36:37], v[32:33], v[38:39]
	v_pk_mul_f32 v[36:37], v[34:35], v[36:37]
	v_cvt_pk_bf16_f32 v224, v36, v37
	global_store_dword v2, v224, s[66:67]
	s_add_u32 s66, s66, 0x2c00
	s_addc_u32 s67, s67, 0
	s_waitcnt vmcnt(61)
	v_lshlrev_b32_e32 v28, 16, v194
	v_and_b32_e32 v29, 0xffff0000, v194
	v_lshlrev_b32_e32 v30, 16, v195
	v_and_b32_e32 v31, 0xffff0000, v195
	v_pk_fma_f32 v[32:33], v[4:5], v[20:21], v[16:17]
	v_pk_fma_f32 v[34:35], v[6:7], v[22:23], v[18:19]
	v_pk_fma_f32 v[32:33], v[8:9], v[24:25], v[32:33]
	v_pk_fma_f32 v[34:35], v[10:11], v[26:27], v[34:35]
	v_pk_fma_f32 v[32:33], v[12:13], v[28:29], v[32:33]
	v_pk_fma_f32 v[34:35], v[14:15], v[30:31], v[34:35]
	v_pk_mul_f32 v[36:37], v[32:33], s[58:59]
	v_pk_mul_f32 v[36:37], v[32:33], v[36:37]
	v_pk_fma_f32 v[36:37], v[32:33], v[36:37], v[32:33]
	v_pk_mul_f32 v[36:37], v[36:37], s[60:61]
	v_pk_mul_f32 v[36:37], v[36:37], s[68:69]
	v_exp_f32_e32 v38, v36
	v_exp_f32_e32 v39, v37
	s_nop 0
	v_pk_add_f32 v[38:39], v[38:39], s[82:83]
	v_rcp_f32_e32 v38, v38
	v_rcp_f32_e32 v39, v39
	s_nop 0
	v_pk_mul_f32 v[36:37], v[32:33], v[38:39]
	v_pk_mul_f32 v[36:37], v[34:35], v[36:37]
	v_cvt_pk_bf16_f32 v224, v36, v37
	global_store_dword v2, v224, s[66:67]
	s_add_u32 s66, s66, 0x2c00
	s_addc_u32 s67, s67, 0
	s_waitcnt vmcnt(60)
; __device__ __forceinline__ float bf2f(unsigned b) { return __uint_as_float(b << 16); }
; __device__ __forceinline__ unsigned pk2(float lo, float hi) { unsigned r; asm("v_cvt_pk_bf16_f32 %0, %1, %2" : "=v"(r) : "v"(lo), "v"(hi)); return r; }
; __device__ __forceinline__ float gelu_t(float x) { return x * __builtin_amdgcn_rcpf(1.f + __expf(-1.5957691216057308f * (x + 0.044715f * x * x * x))); }
; __device__ __forceinline__ void act_item(int item, u16* UP, const u16* HALO, const float* sconv, const float* wconv, const float* bconv, float* out, int lane) {
;     ...
;         for (int t = 0; t < 16; ++t) {
;             const int row = rb * 64 + tb + t;
;             if (sample && (t & 3) == 0) { const int ns = (row - TP) >> 2; const float* s0 = sconv + (size_t)ns * 2 * FF2;
;                 const f32x2 a = *(const f32x2*)(s0 + j0), b = *(const f32x2*)(s0 + FF + j0), c = *(const f32x2*)(s0 + FF2 + j0), dd = *(const f32x2*)(s0 + FF2 + FF + j0);
;                 g2[0] = a.x; g2[1] = a.y; v2[0] = b.x; v2[1] = b.y; g1[0] = c.x; g1[1] = c.y; v1[0] = dd.x; v1[1] = dd.y; }
;             const float g0[2] = {bf2f(gw[t] & 0xffffu), bf2f(gw[t] >> 16)}, v0[2] = {bf2f(vw[t] & 0xffffu), bf2f(vw[t] >> 16)};
;             float res[2];
; #pragma unroll
;             for (int p = 0; p < 2; ++p) { const float cgv = bg[p] + wgt[0][p] * g2[p] + wgt[1][p] * g1[p] + wgt[2][p] * g0[p];
;                 const float cvv = bv[p] + wvl[0][p] * v2[p] + wvl[1][p] * v1[p] + wvl[2][p] * v0[p]; res[p] = gelu_t(cgv) * cvv;
;                 g2[p] = g1[p]; g1[p] = g0[p]; v2[p] = v1[p]; v1[p] = v0[p]; }
;             *(unsigned*)(UP + (size_t)row * FF2 + j0) = pk2(res[0], res[1]);
	v_lshlrev_b32_e32 v20, 16, v196
	v_and_b32_e32 v21, 0xffff0000, v196
	v_lshlrev_b32_e32 v22, 16, v197
	v_and_b32_e32 v23, 0xffff0000, v197
	v_pk_fma_f32 v[32:33], v[4:5], v[24:25], v[16:17]
	v_pk_fma_f32 v[34:35], v[6:7], v[26:27], v[18:19]
	v_pk_fma_f32 v[32:33], v[8:9], v[28:29], v[32:33]
	v_pk_fma_f32 v[34:35], v[10:11], v[30:31], v[34:35]
	v_pk_fma_f32 v[32:33], v[12:13], v[20:21], v[32:33]
	v_pk_fma_f32 v[34:35], v[14:15], v[22:23], v[34:35]
	v_pk_mul_f32 v[36:37], v[32:33], s[58:59]
	v_pk_mul_f32 v[36:37], v[32:33], v[36:37]
	v_pk_fma_f32 v[36:37], v[32:33], v[36:37], v[32:33]
	v_pk_mul_f32 v[36:37], v[36:37], s[60:61]
	v_pk_mul_f32 v[36:37], v[36:37], s[68:69]
	v_exp_f32_e32 v38, v36
	v_exp_f32_e32 v39, v37
	s_nop 0
	v_pk_add_f32 v[38:39], v[38:39], s[82:83]
	v_rcp_f32_e32 v38, v38
	v_rcp_f32_e32 v39, v39
	s_nop 0
	v_pk_mul_f32 v[36:37], v[32:33], v[38:39]
	v_pk_mul_f32 v[36:37], v[34:35], v[36:37]
	v_cvt_pk_bf16_f32 v224, v36, v37
	global_store_dword v2, v224, s[66:67]
	s_add_u32 s66, s66, 0x2c00
	s_addc_u32 s67, s67, 0
	s_waitcnt vmcnt(59)
	v_lshlrev_b32_e32 v24, 16, v198
	v_and_b32_e32 v25, 0xffff0000, v198
	v_lshlrev_b32_e32 v26, 16, v199
	v_and_b32_e32 v27, 0xffff0000, v199
	v_pk_fma_f32 v[32:33], v[4:5], v[28:29], v[16:17]
	v_pk_fma_f32 v[34:35], v[6:7], v[30:31], v[18:19]
	v_pk_fma_f32 v[32:33], v[8:9], v[20:21], v[32:33]
	v_pk_fma_f32 v[34:35], v[10:11], v[22:23], v[34:35]
	v_pk_fma_f32 v[32:33], v[12:13], v[24:25], v[32:33]
	v_pk_fma_f32 v[34:35], v[14:15], v[26:27], v[34:35]
	v_pk_mul_f32 v[36:37], v[32:33], s[58:59]
	v_pk_mul_f32 v[36:37], v[32:33], v[36:37]
	v_pk_fma_f32 v[36:37], v[32:33], v[36:37], v[32:33]
	v_pk_mul_f32 v[36:37], v[36:37], s[60:61]
	v_pk_mul_f32 v[36:37], v[36:37], s[68:69]
	v_exp_f32_e32 v38, v36
	v_exp_f32_e32 v39, v37
	s_nop 0
	v_pk_add_f32 v[38:39], v[38:39], s[82:83]
	v_rcp_f32_e32 v38, v38
	v_rcp_f32_e32 v39, v39
	s_nop 0
	v_pk_mul_f32 v[36:37], v[32:33], v[38:39]
	v_pk_mul_f32 v[36:37], v[34:35], v[36:37]
	v_cvt_pk_bf16_f32 v224, v36, v37
	global_store_dword v2, v224, s[66:67]
	s_add_u32 s66, s66, 0x2c00
	s_addc_u32 s67, s67, 0
	s_waitcnt vmcnt(58)
	v_lshlrev_b32_e32 v28, 16, v200
	v_and_b32_e32 v29, 0xffff0000, v200
	v_lshlrev_b32_e32 v30, 16, v201
	v_and_b32_e32 v31, 0xffff0000, v201
	v_pk_fma_f32 v[32:33], v[4:5], v[20:21], v[16:17]
	v_pk_fma_f32 v[34:35], v[6:7], v[22:23], v[18:19]
	v_pk_fma_f32 v[32:33], v[8:9], v[24:25], v[32:33]
	v_pk_fma_f32 v[34:35], v[10:11], v[26:27], v[34:35]
	v_pk_fma_f32 v[32:33], v[12:13], v[28:29], v[32:33]
	v_pk_fma_f32 v[34:35], v[14:15], v[30:31], v[34:35]
	v_pk_mul_f32 v[36:37], v[32:33], s[58:59]
	v_pk_mul_f32 v[36:37], v[32:33], v[36:37]
	v_pk_fma_f32 v[36:37], v[32:33], v[36:37], v[32:33]
	v_pk_mul_f32 v[36:37], v[36:37], s[60:61]
	v_pk_mul_f32 v[36:37], v[36:37], s[68:69]
	v_exp_f32_e32 v38, v36
	v_exp_f32_e32 v39, v37
	s_nop 0
	v_pk_add_f32 v[38:39], v[38:39], s[82:83]
	v_rcp_f32_e32 v38, v38
	v_rcp_f32_e32 v39, v39
	s_nop 0
	v_pk_mul_f32 v[36:37], v[32:33], v[38:39]
	v_pk_mul_f32 v[36:37], v[34:35], v[36:37]
	v_cvt_pk_bf16_f32 v224, v36, v37
	global_store_dword v2, v224, s[66:67]
	s_add_u32 s66, s66, 0x2c00
	s_addc_u32 s67, s67, 0
	s_waitcnt vmcnt(57)
	v_lshlrev_b32_e32 v20, 16, v202
	v_and_b32_e32 v21, 0xffff0000, v202
	v_lshlrev_b32_e32 v22, 16, v203
	v_and_b32_e32 v23, 0xffff0000, v203
	v_pk_fma_f32 v[32:33], v[4:5], v[24:25], v[16:17]
	v_pk_fma_f32 v[34:35], v[6:7], v[26:27], v[18:19]
	v_pk_fma_f32 v[32:33], v[8:9], v[28:29], v[32:33]
	v_pk_fma_f32 v[34:35], v[10:11], v[30:31], v[34:35]
	v_pk_fma_f32 v[32:33], v[12:13], v[20:21], v[32:33]
	v_pk_fma_f32 v[34:35], v[14:15], v[22:23], v[34:35]
	v_pk_mul_f32 v[36:37], v[32:33], s[58:59]
	v_pk_mul_f32 v[36:37], v[32:33], v[36:37]
	v_pk_fma_f32 v[36:37], v[32:33], v[36:37], v[32:33]
	v_pk_mul_f32 v[36:37], v[36:37], s[60:61]
	v_pk_mul_f32 v[36:37], v[36:37], s[68:69]
	v_exp_f32_e32 v38, v36
	v_exp_f32_e32 v39, v37
	s_nop 0
	v_pk_add_f32 v[38:39], v[38:39], s[82:83]
	v_rcp_f32_e32 v38, v38
	v_rcp_f32_e32 v39, v39
	s_nop 0
	v_pk_mul_f32 v[36:37], v[32:33], v[38:39]
	v_pk_mul_f32 v[36:37], v[34:35], v[36:37]
	v_cvt_pk_bf16_f32 v224, v36, v37
	global_store_dword v2, v224, s[66:67]
	s_add_u32 s66, s66, 0x2c00
	s_addc_u32 s67, s67, 0
	s_waitcnt vmcnt(56)
	v_lshlrev_b32_e32 v24, 16, v204
	v_and_b32_e32 v25, 0xffff0000, v204
	v_lshlrev_b32_e32 v26, 16, v205
	v_and_b32_e32 v27, 0xffff0000, v205
	v_pk_fma_f32 v[32:33], v[4:5], v[28:29], v[16:17]
	v_pk_fma_f32 v[34:35], v[6:7], v[30:31], v[18:19]
	v_pk_fma_f32 v[32:33], v[8:9], v[20:21], v[32:33]
	v_pk_fma_f32 v[34:35], v[10:11], v[22:23], v[34:35]
	v_pk_fma_f32 v[32:33], v[12:13], v[24:25], v[32:33]
	v_pk_fma_f32 v[34:35], v[14:15], v[26:27], v[34:35]
	v_pk_mul_f32 v[36:37], v[32:33], s[58:59]
	v_pk_mul_f32 v[36:37], v[32:33], v[36:37]
	v_pk_fma_f32 v[36:37], v[32:33], v[36:37], v[32:33]
	v_pk_mul_f32 v[36:37], v[36:37], s[60:61]
	v_pk_mul_f32 v[36:37], v[36:37], s[68:69]
	v_exp_f32_e32 v38, v36
	v_exp_f32_e32 v39, v37
	s_nop 0
	v_pk_add_f32 v[38:39], v[38:39], s[82:83]
	v_rcp_f32_e32 v38, v38
	v_rcp_f32_e32 v39, v39
	s_nop 0
	v_pk_mul_f32 v[36:37], v[32:33], v[38:39]
	v_pk_mul_f32 v[36:37], v[34:35], v[36:37]
	v_cvt_pk_bf16_f32 v224, v36, v37
	global_store_dword v2, v224, s[66:67]
	s_add_u32 s66, s66, 0x2c00
	s_addc_u32 s67, s67, 0
	s_waitcnt vmcnt(55)
; __device__ __forceinline__ float bf2f(unsigned b) { return __uint_as_float(b << 16); }
; __device__ __forceinline__ unsigned pk2(float lo, float hi) { unsigned r; asm("v_cvt_pk_bf16_f32 %0, %1, %2" : "=v"(r) : "v"(lo), "v"(hi)); return r; }
; __device__ __forceinline__ float gelu_t(float x) { return x * __builtin_amdgcn_rcpf(1.f + __expf(-1.5957691216057308f * (x + 0.044715f * x * x * x))); }
; __device__ __forceinline__ void act_item(int item, u16* UP, const u16* HALO, const float* sconv, const float* wconv, const float* bconv, float* out, int lane) {
;     ...
;         for (int t = 0; t < 16; ++t) {
;             const int row = rb * 64 + tb + t;
;             if (sample && (t & 3) == 0) { const int ns = (row - TP) >> 2; const float* s0 = sconv + (size_t)ns * 2 * FF2;
;                 const f32x2 a = *(const f32x2*)(s0 + j0), b = *(const f32x2*)(s0 + FF + j0), c = *(const f32x2*)(s0 + FF2 + j0), dd = *(const f32x2*)(s0 + FF2 + FF + j0);
;                 g2[0] = a.x; g2[1] = a.y; v2[0] = b.x; v2[1] = b.y; g1[0] = c.x; g1[1] = c.y; v1[0] = dd.x; v1[1] = dd.y; }
;             const float g0[2] = {bf2f(gw[t] & 0xffffu), bf2f(gw[t] >> 16)}, v0[2] = {bf2f(vw[t] & 0xffffu), bf2f(vw[t] >> 16)};
;             float res[2];
; #pragma unroll
;             for (int p = 0; p < 2; ++p) { const float cgv = bg[p] + wgt[0][p] * g2[p] + wgt[1][p] * g1[p] + wgt[2][p] * g0[p];
;                 const float cvv = bv[p] + wvl[0][p] * v2[p] + wvl[1][p] * v1[p] + wvl[2][p] * v0[p]; res[p] = gelu_t(cgv) * cvv;
;                 g2[p] = g1[p]; g1[p] = g0[p]; v2[p] = v1[p]; v1[p] = v0[p]; }
;             *(unsigned*)(UP + (size_t)row * FF2 + j0) = pk2(res[0], res[1]);
	v_lshlrev_b32_e32 v28, 16, v206
	v_and_b32_e32 v29, 0xffff0000, v206
	v_lshlrev_b32_e32 v30, 16, v207
	v_and_b32_e32 v31, 0xffff0000, v207
	v_pk_fma_f32 v[32:33], v[4:5], v[20:21], v[16:17]
	v_pk_fma_f32 v[34:35], v[6:7], v[22:23], v[18:19]
	v_pk_fma_f32 v[32:33], v[8:9], v[24:25], v[32:33]
	v_pk_fma_f32 v[34:35], v[10:11], v[26:27], v[34:35]
	v_pk_fma_f32 v[32:33], v[12:13], v[28:29], v[32:33]
	v_pk_fma_f32 v[34:35], v[14:15], v[30:31], v[34:35]
	v_pk_mul_f32 v[36:37], v[32:33], s[58:59]
	v_pk_mul_f32 v[36:37], v[32:33], v[36:37]
	v_pk_fma_f32 v[36:37], v[32:33], v[36:37], v[32:33]
	v_pk_mul_f32 v[36:37], v[36:37], s[60:61]
	v_pk_mul_f32 v[36:37], v[36:37], s[68:69]
	v_exp_f32_e32 v38, v36
	v_exp_f32_e32 v39, v37
	s_nop 0
	v_pk_add_f32 v[38:39], v[38:39], s[82:83]
	v_rcp_f32_e32 v38, v38
	v_rcp_f32_e32 v39, v39
	s_nop 0
	v_pk_mul_f32 v[36:37], v[32:33], v[38:39]
	v_pk_mul_f32 v[36:37], v[34:35], v[36:37]
	v_cvt_pk_bf16_f32 v224, v36, v37
	global_store_dword v2, v224, s[66:67]
	s_add_u32 s66, s66, 0x2c00
	s_addc_u32 s67, s67, 0
	s_waitcnt vmcnt(54)
	v_lshlrev_b32_e32 v20, 16, v208
	v_and_b32_e32 v21, 0xffff0000, v208
	v_lshlrev_b32_e32 v22, 16, v209
	v_and_b32_e32 v23, 0xffff0000, v209
	v_pk_fma_f32 v[32:33], v[4:5], v[24:25], v[16:17]
	v_pk_fma_f32 v[34:35], v[6:7], v[26:27], v[18:19]
	v_pk_fma_f32 v[32:33], v[8:9], v[28:29], v[32:33]
	v_pk_fma_f32 v[34:35], v[10:11], v[30:31], v[34:35]
	v_pk_fma_f32 v[32:33], v[12:13], v[20:21], v[32:33]
	v_pk_fma_f32 v[34:35], v[14:15], v[22:23], v[34:35]
	v_pk_mul_f32 v[36:37], v[32:33], s[58:59]
	v_pk_mul_f32 v[36:37], v[32:33], v[36:37]
	v_pk_fma_f32 v[36:37], v[32:33], v[36:37], v[32:33]
	v_pk_mul_f32 v[36:37], v[36:37], s[60:61]
	v_pk_mul_f32 v[36:37], v[36:37], s[68:69]
	v_exp_f32_e32 v38, v36
	v_exp_f32_e32 v39, v37
	s_nop 0
	v_pk_add_f32 v[38:39], v[38:39], s[82:83]
	v_rcp_f32_e32 v38, v38
	v_rcp_f32_e32 v39, v39
	s_nop 0
	v_pk_mul_f32 v[36:37], v[32:33], v[38:39]
	v_pk_mul_f32 v[36:37], v[34:35], v[36:37]
	v_cvt_pk_bf16_f32 v224, v36, v37
	global_store_dword v2, v224, s[66:67]
	s_add_u32 s66, s66, 0x2c00
	s_addc_u32 s67, s67, 0
	s_waitcnt vmcnt(53)
	v_lshlrev_b32_e32 v24, 16, v210
	v_and_b32_e32 v25, 0xffff0000, v210
	v_lshlrev_b32_e32 v26, 16, v211
	v_and_b32_e32 v27, 0xffff0000, v211
	v_pk_fma_f32 v[32:33], v[4:5], v[28:29], v[16:17]
	v_pk_fma_f32 v[34:35], v[6:7], v[30:31], v[18:19]
	v_pk_fma_f32 v[32:33], v[8:9], v[20:21], v[32:33]
	v_pk_fma_f32 v[34:35], v[10:11], v[22:23], v[34:35]
	v_pk_fma_f32 v[32:33], v[12:13], v[24:25], v[32:33]
	v_pk_fma_f32 v[34:35], v[14:15], v[26:27], v[34:35]
	v_pk_mul_f32 v[36:37], v[32:33], s[58:59]
	v_pk_mul_f32 v[36:37], v[32:33], v[36:37]
	v_pk_fma_f32 v[36:37], v[32:33], v[36:37], v[32:33]
	v_pk_mul_f32 v[36:37], v[36:37], s[60:61]
	v_pk_mul_f32 v[36:37], v[36:37], s[68:69]
	v_exp_f32_e32 v38, v36
	v_exp_f32_e32 v39, v37
	s_nop 0
	v_pk_add_f32 v[38:39], v[38:39], s[82:83]
	v_rcp_f32_e32 v38, v38
	v_rcp_f32_e32 v39, v39
	s_nop 0
	v_pk_mul_f32 v[36:37], v[32:33], v[38:39]
	v_pk_mul_f32 v[36:37], v[34:35], v[36:37]
	v_cvt_pk_bf16_f32 v224, v36, v37
	global_store_dword v2, v224, s[66:67]
	s_add_u32 s66, s66, 0x2c00
	s_addc_u32 s67, s67, 0
	s_waitcnt vmcnt(52)
	v_lshlrev_b32_e32 v28, 16, v212
	v_and_b32_e32 v29, 0xffff0000, v212
	v_lshlrev_b32_e32 v30, 16, v213
	v_and_b32_e32 v31, 0xffff0000, v213
	v_pk_fma_f32 v[32:33], v[4:5], v[20:21], v[16:17]
	v_pk_fma_f32 v[34:35], v[6:7], v[22:23], v[18:19]
	v_pk_fma_f32 v[32:33], v[8:9], v[24:25], v[32:33]
	v_pk_fma_f32 v[34:35], v[10:11], v[26:27], v[34:35]
	v_pk_fma_f32 v[32:33], v[12:13], v[28:29], v[32:33]
	v_pk_fma_f32 v[34:35], v[14:15], v[30:31], v[34:35]
	v_pk_mul_f32 v[36:37], v[32:33], s[58:59]
	v_pk_mul_f32 v[36:37], v[32:33], v[36:37]
	v_pk_fma_f32 v[36:37], v[32:33], v[36:37], v[32:33]
	v_pk_mul_f32 v[36:37], v[36:37], s[60:61]
	v_pk_mul_f32 v[36:37], v[36:37], s[68:69]
	v_exp_f32_e32 v38, v36
	v_exp_f32_e32 v39, v37
	s_nop 0
	v_pk_add_f32 v[38:39], v[38:39], s[82:83]
	v_rcp_f32_e32 v38, v38
	v_rcp_f32_e32 v39, v39
	s_nop 0
	v_pk_mul_f32 v[36:37], v[32:33], v[38:39]
	v_pk_mul_f32 v[36:37], v[34:35], v[36:37]
	v_cvt_pk_bf16_f32 v224, v36, v37
	global_store_dword v2, v224, s[66:67]
	s_add_u32 s66, s66, 0x2c00
	s_addc_u32 s67, s67, 0
	s_waitcnt vmcnt(51)
	v_lshlrev_b32_e32 v20, 16, v214
	v_and_b32_e32 v21, 0xffff0000, v214
	v_lshlrev_b32_e32 v22, 16, v215
	v_and_b32_e32 v23, 0xffff0000, v215
	v_pk_fma_f32 v[32:33], v[4:5], v[24:25], v[16:17]
	v_pk_fma_f32 v[34:35], v[6:7], v[26:27], v[18:19]
	v_pk_fma_f32 v[32:33], v[8:9], v[28:29], v[32:33]
	v_pk_fma_f32 v[34:35], v[10:11], v[30:31], v[34:35]
	v_pk_fma_f32 v[32:33], v[12:13], v[20:21], v[32:33]
	v_pk_fma_f32 v[34:35], v[14:15], v[22:23], v[34:35]
	v_pk_mul_f32 v[36:37], v[32:33], s[58:59]
	v_pk_mul_f32 v[36:37], v[32:33], v[36:37]
	v_pk_fma_f32 v[36:37], v[32:33], v[36:37], v[32:33]
	v_pk_mul_f32 v[36:37], v[36:37], s[60:61]
	v_pk_mul_f32 v[36:37], v[36:37], s[68:69]
	v_exp_f32_e32 v38, v36
	v_exp_f32_e32 v39, v37
	s_nop 0
	v_pk_add_f32 v[38:39], v[38:39], s[82:83]
	v_rcp_f32_e32 v38, v38
	v_rcp_f32_e32 v39, v39
	s_nop 0
	v_pk_mul_f32 v[36:37], v[32:33], v[38:39]
	v_pk_mul_f32 v[36:37], v[34:35], v[36:37]
	v_cvt_pk_bf16_f32 v224, v36, v37
	global_store_dword v2, v224, s[66:67]
	s_add_u32 s66, s66, 0x2c00
	s_addc_u32 s67, s67, 0
	s_waitcnt vmcnt(50)
; __device__ __forceinline__ float bf2f(unsigned b) { return __uint_as_float(b << 16); }
; __device__ __forceinline__ unsigned pk2(float lo, float hi) { unsigned r; asm("v_cvt_pk_bf16_f32 %0, %1, %2" : "=v"(r) : "v"(lo), "v"(hi)); return r; }
; __device__ __forceinline__ float gelu_t(float x) { return x * __builtin_amdgcn_rcpf(1.f + __expf(-1.5957691216057308f * (x + 0.044715f * x * x * x))); }
; __device__ __forceinline__ void act_item(int item, u16* UP, const u16* HALO, const float* sconv, const float* wconv, const float* bconv, float* out, int lane) {
;     ...
;         for (int t = 0; t < 16; ++t) { const size_t row = (size_t)rb * 64 + tb + t; gw[t] = *(const unsigned*)(UP + row * FF2 + j0); vw[t] = *(const unsigned*)(UP + row * FF2 + FF + j0); }
; #pragma unroll
;         for (int t = 0; t < 16; ++t) {
;             const int row = rb * 64 + tb + t;
;             if (sample && (t & 3) == 0) { const int ns = (row - TP) >> 2; const float* s0 = sconv + (size_t)ns * 2 * FF2;
;                 const f32x2 a = *(const f32x2*)(s0 + j0), b = *(const f32x2*)(s0 + FF + j0), c = *(const f32x2*)(s0 + FF2 + j0), dd = *(const f32x2*)(s0 + FF2 + FF + j0);
;                 g2[0] = a.x; g2[1] = a.y; v2[0] = b.x; v2[1] = b.y; g1[0] = c.x; g1[1] = c.y; v1[0] = dd.x; v1[1] = dd.y; }
;             const float g0[2] = {bf2f(gw[t] & 0xffffu), bf2f(gw[t] >> 16)}, v0[2] = {bf2f(vw[t] & 0xffffu), bf2f(vw[t] >> 16)};
;             float res[2];
; #pragma unroll
;             for (int p = 0; p < 2; ++p) { const float cgv = bg[p] + wgt[0][p] * g2[p] + wgt[1][p] * g1[p] + wgt[2][p] * g0[p];
;                 const float cvv = bv[p] + wvl[0][p] * v2[p] + wvl[1][p] * v1[p] + wvl[2][p] * v0[p]; res[p] = gelu_t(cgv) * cvv;
;                 g2[p] = g1[p]; g1[p] = g0[p]; v2[p] = v1[p]; v1[p] = v0[p]; }
;             *(unsigned*)(UP + (size_t)row * FF2 + j0) = pk2(res[0], res[1]);
	v_lshlrev_b32_e32 v24, 16, v216
	v_and_b32_e32 v25, 0xffff0000, v216
	v_lshlrev_b32_e32 v26, 16, v217
	v_and_b32_e32 v27, 0xffff0000, v217
	v_pk_fma_f32 v[32:33], v[4:5], v[28:29], v[16:17]
	v_pk_fma_f32 v[34:35], v[6:7], v[30:31], v[18:19]
	v_pk_fma_f32 v[32:33], v[8:9], v[20:21], v[32:33]
	v_pk_fma_f32 v[34:35], v[10:11], v[22:23], v[34:35]
	v_pk_fma_f32 v[32:33], v[12:13], v[24:25], v[32:33]
	v_pk_fma_f32 v[34:35], v[14:15], v[26:27], v[34:35]
	v_pk_mul_f32 v[36:37], v[32:33], s[58:59]
	v_pk_mul_f32 v[36:37], v[32:33], v[36:37]
	v_pk_fma_f32 v[36:37], v[32:33], v[36:37], v[32:33]
	v_pk_mul_f32 v[36:37], v[36:37], s[60:61]
	v_pk_mul_f32 v[36:37], v[36:37], s[68:69]
	v_exp_f32_e32 v38, v36
	v_exp_f32_e32 v39, v37
	s_nop 0
	v_pk_add_f32 v[38:39], v[38:39], s[82:83]
	v_rcp_f32_e32 v38, v38
	v_rcp_f32_e32 v39, v39
	s_nop 0
	v_pk_mul_f32 v[36:37], v[32:33], v[38:39]
	v_pk_mul_f32 v[36:37], v[34:35], v[36:37]
	v_cvt_pk_bf16_f32 v224, v36, v37
	global_store_dword v2, v224, s[66:67]
	s_add_u32 s66, s66, 0x2c00
	s_addc_u32 s67, s67, 0
	s_waitcnt vmcnt(49)
	v_lshlrev_b32_e32 v28, 16, v218
	v_and_b32_e32 v29, 0xffff0000, v218
	v_lshlrev_b32_e32 v30, 16, v219
	v_and_b32_e32 v31, 0xffff0000, v219
	v_pk_fma_f32 v[32:33], v[4:5], v[20:21], v[16:17]
	v_pk_fma_f32 v[34:35], v[6:7], v[22:23], v[18:19]
	v_pk_fma_f32 v[32:33], v[8:9], v[24:25], v[32:33]
	v_pk_fma_f32 v[34:35], v[10:11], v[26:27], v[34:35]
	v_pk_fma_f32 v[32:33], v[12:13], v[28:29], v[32:33]
	v_pk_fma_f32 v[34:35], v[14:15], v[30:31], v[34:35]
	v_pk_mul_f32 v[36:37], v[32:33], s[58:59]
	v_pk_mul_f32 v[36:37], v[32:33], v[36:37]
	v_pk_fma_f32 v[36:37], v[32:33], v[36:37], v[32:33]
	v_pk_mul_f32 v[36:37], v[36:37], s[60:61]
	v_pk_mul_f32 v[36:37], v[36:37], s[68:69]
	v_exp_f32_e32 v38, v36
	v_exp_f32_e32 v39, v37
	s_nop 0
	v_pk_add_f32 v[38:39], v[38:39], s[82:83]
	v_rcp_f32_e32 v38, v38
	v_rcp_f32_e32 v39, v39
	s_nop 0
	v_pk_mul_f32 v[36:37], v[32:33], v[38:39]
	v_pk_mul_f32 v[36:37], v[34:35], v[36:37]
	v_cvt_pk_bf16_f32 v224, v36, v37
	global_store_dword v2, v224, s[66:67]
	s_add_u32 s66, s66, 0x2c00
	s_addc_u32 s67, s67, 0
	s_waitcnt vmcnt(48)
	v_lshlrev_b32_e32 v20, 16, v220
	v_and_b32_e32 v21, 0xffff0000, v220
	v_lshlrev_b32_e32 v22, 16, v221
	v_and_b32_e32 v23, 0xffff0000, v221
	v_pk_fma_f32 v[32:33], v[4:5], v[24:25], v[16:17]
	v_pk_fma_f32 v[34:35], v[6:7], v[26:27], v[18:19]
	v_pk_fma_f32 v[32:33], v[8:9], v[28:29], v[32:33]
	v_pk_fma_f32 v[34:35], v[10:11], v[30:31], v[34:35]
	v_pk_fma_f32 v[32:33], v[12:13], v[20:21], v[32:33]
	v_pk_fma_f32 v[34:35], v[14:15], v[22:23], v[34:35]
	v_pk_mul_f32 v[36:37], v[32:33], s[58:59]
	v_pk_mul_f32 v[36:37], v[32:33], v[36:37]
	v_pk_fma_f32 v[36:37], v[32:33], v[36:37], v[32:33]
	v_pk_mul_f32 v[36:37], v[36:37], s[60:61]
	v_pk_mul_f32 v[36:37], v[36:37], s[68:69]
	v_exp_f32_e32 v38, v36
	v_exp_f32_e32 v39, v37
	s_nop 0
	v_pk_add_f32 v[38:39], v[38:39], s[82:83]
	v_rcp_f32_e32 v38, v38
	v_rcp_f32_e32 v39, v39
	s_nop 0
	v_pk_mul_f32 v[36:37], v[32:33], v[38:39]
	v_pk_mul_f32 v[36:37], v[34:35], v[36:37]
	v_cvt_pk_bf16_f32 v224, v36, v37
	global_store_dword v2, v224, s[66:67]
	s_add_u32 s66, s66, 0x2c00
	s_addc_u32 s67, s67, 0
	s_waitcnt vmcnt(47)
	v_lshlrev_b32_e32 v24, 16, v222
	v_and_b32_e32 v25, 0xffff0000, v222
	v_lshlrev_b32_e32 v26, 16, v223
	v_and_b32_e32 v27, 0xffff0000, v223
	v_pk_fma_f32 v[32:33], v[4:5], v[28:29], v[16:17]
	v_pk_fma_f32 v[34:35], v[6:7], v[30:31], v[18:19]
	v_pk_fma_f32 v[32:33], v[8:9], v[20:21], v[32:33]
	v_pk_fma_f32 v[34:35], v[10:11], v[22:23], v[34:35]
	v_pk_fma_f32 v[32:33], v[12:13], v[24:25], v[32:33]
	v_pk_fma_f32 v[34:35], v[14:15], v[26:27], v[34:35]
	v_pk_mul_f32 v[36:37], v[32:33], s[58:59]
	v_pk_mul_f32 v[36:37], v[32:33], v[36:37]
	v_pk_fma_f32 v[36:37], v[32:33], v[36:37], v[32:33]
	v_pk_mul_f32 v[36:37], v[36:37], s[60:61]
	v_pk_mul_f32 v[36:37], v[36:37], s[68:69]
	v_exp_f32_e32 v38, v36
	v_exp_f32_e32 v39, v37
	s_nop 0
	v_pk_add_f32 v[38:39], v[38:39], s[82:83]
	v_rcp_f32_e32 v38, v38
	v_rcp_f32_e32 v39, v39
	s_nop 0
	v_pk_mul_f32 v[36:37], v[32:33], v[38:39]
	v_pk_mul_f32 v[36:37], v[34:35], v[36:37]
	v_cvt_pk_bf16_f32 v224, v36, v37
	global_store_dword v2, v224, s[66:67]
	s_add_u32 s66, s66, 0x2c00
	s_addc_u32 s67, s67, 0
	global_load_dword v192, v2, s[64:65]
	global_load_dword v193, v3, s[64:65]
	s_add_u32 s64, s64, 0x2c00
	s_addc_u32 s65, s65, 0
	global_load_dword v194, v2, s[64:65]
	global_load_dword v195, v3, s[64:65]
	s_add_u32 s64, s64, 0x2c00
	s_addc_u32 s65, s65, 0
	global_load_dword v196, v2, s[64:65]
	global_load_dword v197, v3, s[64:65]
	s_add_u32 s64, s64, 0x2c00
	s_addc_u32 s65, s65, 0
	global_load_dword v198, v2, s[64:65]
	global_load_dword v199, v3, s[64:65]
	s_add_u32 s64, s64, 0x2c00
	s_addc_u32 s65, s65, 0
	global_load_dword v200, v2, s[64:65]
	global_load_dword v201, v3, s[64:65]
	s_add_u32 s64, s64, 0x2c00
	s_addc_u32 s65, s65, 0
	global_load_dword v202, v2, s[64:65]
	global_load_dword v203, v3, s[64:65]
	s_add_u32 s64, s64, 0x2c00
	s_addc_u32 s65, s65, 0
	global_load_dword v204, v2, s[64:65]
	global_load_dword v205, v3, s[64:65]
	s_add_u32 s64, s64, 0x2c00
	s_addc_u32 s65, s65, 0
	global_load_dword v206, v2, s[64:65]
	global_load_dword v207, v3, s[64:65]
	s_add_u32 s64, s64, 0x2c00
	s_addc_u32 s65, s65, 0
	global_load_dword v208, v2, s[64:65]
	global_load_dword v209, v3, s[64:65]
	s_add_u32 s64, s64, 0x2c00
	s_addc_u32 s65, s65, 0
	global_load_dword v210, v2, s[64:65]
	global_load_dword v211, v3, s[64:65]
	s_add_u32 s64, s64, 0x2c00
	s_addc_u32 s65, s65, 0
	global_load_dword v212, v2, s[64:65]
	global_load_dword v213, v3, s[64:65]
	s_add_u32 s64, s64, 0x2c00
	s_addc_u32 s65, s65, 0
	global_load_dword v214, v2, s[64:65]
	global_load_dword v215, v3, s[64:65]
	s_add_u32 s64, s64, 0x2c00
	s_addc_u32 s65, s65, 0
	global_load_dword v216, v2, s[64:65]
	global_load_dword v217, v3, s[64:65]
	s_add_u32 s64, s64, 0x2c00
	s_addc_u32 s65, s65, 0
	global_load_dword v218, v2, s[64:65]
	global_load_dword v219, v3, s[64:65]
	s_add_u32 s64, s64, 0x2c00
	s_addc_u32 s65, s65, 0
	global_load_dword v220, v2, s[64:65]
	global_load_dword v221, v3, s[64:65]
	s_add_u32 s64, s64, 0x2c00
	s_addc_u32 s65, s65, 0
	global_load_dword v222, v2, s[64:65]
	global_load_dword v223, v3, s[64:65]
	s_add_u32 s64, s64, 0x2c00
	s_addc_u32 s65, s65, 0
	s_waitcnt vmcnt(62)
; __device__ __forceinline__ float bf2f(unsigned b) { return __uint_as_float(b << 16); }
; __device__ __forceinline__ unsigned pk2(float lo, float hi) { unsigned r; asm("v_cvt_pk_bf16_f32 %0, %1, %2" : "=v"(r) : "v"(lo), "v"(hi)); return r; }
; __device__ __forceinline__ float gelu_t(float x) { return x * __builtin_amdgcn_rcpf(1.f + __expf(-1.5957691216057308f * (x + 0.044715f * x * x * x))); }
; __device__ __forceinline__ void act_item(int item, u16* UP, const u16* HALO, const float* sconv, const float* wconv, const float* bconv, float* out, int lane) {
;     ...
;         for (int t = 0; t < 16; ++t) {
;             const int row = rb * 64 + tb + t;
;             if (sample && (t & 3) == 0) { const int ns = (row - TP) >> 2; const float* s0 = sconv + (size_t)ns * 2 * FF2;
;                 const f32x2 a = *(const f32x2*)(s0 + j0), b = *(const f32x2*)(s0 + FF + j0), c = *(const f32x2*)(s0 + FF2 + j0), dd = *(const f32x2*)(s0 + FF2 + FF + j0);
;                 g2[0] = a.x; g2[1] = a.y; v2[0] = b.x; v2[1] = b.y; g1[0] = c.x; g1[1] = c.y; v1[0] = dd.x; v1[1] = dd.y; }
;             const float g0[2] = {bf2f(gw[t] & 0xffffu), bf2f(gw[t] >> 16)}, v0[2] = {bf2f(vw[t] & 0xffffu), bf2f(vw[t] >> 16)};
;             float res[2];
; #pragma unroll
;             for (int p = 0; p < 2; ++p) { const float cgv = bg[p] + wgt[0][p] * g2[p] + wgt[1][p] * g1[p] + wgt[2][p] * g0[p];
;                 const float cvv = bv[p] + wvl[0][p] * v2[p] + wvl[1][p] * v1[p] + wvl[2][p] * v0[p]; res[p] = gelu_t(cgv) * cvv;
;                 g2[p] = g1[p]; g1[p] = g0[p]; v2[p] = v1[p]; v1[p] = v0[p]; }
;             *(unsigned*)(UP + (size_t)row * FF2 + j0) = pk2(res[0], res[1]);
	v_lshlrev_b32_e32 v28, 16, v160
	v_and_b32_e32 v29, 0xffff0000, v160
	v_lshlrev_b32_e32 v30, 16, v161
	v_and_b32_e32 v31, 0xffff0000, v161
	v_pk_fma_f32 v[32:33], v[4:5], v[20:21], v[16:17]
	v_pk_fma_f32 v[34:35], v[6:7], v[22:23], v[18:19]
	v_pk_fma_f32 v[32:33], v[8:9], v[24:25], v[32:33]
	v_pk_fma_f32 v[34:35], v[10:11], v[26:27], v[34:35]
	v_pk_fma_f32 v[32:33], v[12:13], v[28:29], v[32:33]
	v_pk_fma_f32 v[34:35], v[14:15], v[30:31], v[34:35]
	v_pk_mul_f32 v[36:37], v[32:33], s[58:59]
	v_pk_mul_f32 v[36:37], v[32:33], v[36:37]
	v_pk_fma_f32 v[36:37], v[32:33], v[36:37], v[32:33]
	v_pk_mul_f32 v[36:37], v[36:37], s[60:61]
	v_pk_mul_f32 v[36:37], v[36:37], s[68:69]
	v_exp_f32_e32 v38, v36
	v_exp_f32_e32 v39, v37
	s_nop 0
	v_pk_add_f32 v[38:39], v[38:39], s[82:83]
	v_rcp_f32_e32 v38, v38
	v_rcp_f32_e32 v39, v39
	s_nop 0
	v_pk_mul_f32 v[36:37], v[32:33], v[38:39]
	v_pk_mul_f32 v[36:37], v[34:35], v[36:37]
	v_cvt_pk_bf16_f32 v224, v36, v37
	global_store_dword v2, v224, s[66:67]
	s_add_u32 s66, s66, 0x2c00
	s_addc_u32 s67, s67, 0
	s_waitcnt vmcnt(61)
	v_lshlrev_b32_e32 v20, 16, v162
	v_and_b32_e32 v21, 0xffff0000, v162
	v_lshlrev_b32_e32 v22, 16, v163
	v_and_b32_e32 v23, 0xffff0000, v163
	v_pk_fma_f32 v[32:33], v[4:5], v[24:25], v[16:17]
	v_pk_fma_f32 v[34:35], v[6:7], v[26:27], v[18:19]
	v_pk_fma_f32 v[32:33], v[8:9], v[28:29], v[32:33]
	v_pk_fma_f32 v[34:35], v[10:11], v[30:31], v[34:35]
	v_pk_fma_f32 v[32:33], v[12:13], v[20:21], v[32:33]
	v_pk_fma_f32 v[34:35], v[14:15], v[22:23], v[34:35]
	v_pk_mul_f32 v[36:37], v[32:33], s[58:59]
	v_pk_mul_f32 v[36:37], v[32:33], v[36:37]
	v_pk_fma_f32 v[36:37], v[32:33], v[36:37], v[32:33]
	v_pk_mul_f32 v[36:37], v[36:37], s[60:61]
	v_pk_mul_f32 v[36:37], v[36:37], s[68:69]
	v_exp_f32_e32 v38, v36
	v_exp_f32_e32 v39, v37
	s_nop 0
	v_pk_add_f32 v[38:39], v[38:39], s[82:83]
	v_rcp_f32_e32 v38, v38
	v_rcp_f32_e32 v39, v39
	s_nop 0
	v_pk_mul_f32 v[36:37], v[32:33], v[38:39]
	v_pk_mul_f32 v[36:37], v[34:35], v[36:37]
	v_cvt_pk_bf16_f32 v224, v36, v37
	global_store_dword v2, v224, s[66:67]
	s_add_u32 s66, s66, 0x2c00
	s_addc_u32 s67, s67, 0
	s_waitcnt vmcnt(60)
	v_lshlrev_b32_e32 v24, 16, v164
	v_and_b32_e32 v25, 0xffff0000, v164
	v_lshlrev_b32_e32 v26, 16, v165
	v_and_b32_e32 v27, 0xffff0000, v165
	v_pk_fma_f32 v[32:33], v[4:5], v[28:29], v[16:17]
	v_pk_fma_f32 v[34:35], v[6:7], v[30:31], v[18:19]
	v_pk_fma_f32 v[32:33], v[8:9], v[20:21], v[32:33]
	v_pk_fma_f32 v[34:35], v[10:11], v[22:23], v[34:35]
	v_pk_fma_f32 v[32:33], v[12:13], v[24:25], v[32:33]
	v_pk_fma_f32 v[34:35], v[14:15], v[26:27], v[34:35]
	v_pk_mul_f32 v[36:37], v[32:33], s[58:59]
	v_pk_mul_f32 v[36:37], v[32:33], v[36:37]
	v_pk_fma_f32 v[36:37], v[32:33], v[36:37], v[32:33]
	v_pk_mul_f32 v[36:37], v[36:37], s[60:61]
	v_pk_mul_f32 v[36:37], v[36:37], s[68:69]
	v_exp_f32_e32 v38, v36
	v_exp_f32_e32 v39, v37
	s_nop 0
	v_pk_add_f32 v[38:39], v[38:39], s[82:83]
	v_rcp_f32_e32 v38, v38
	v_rcp_f32_e32 v39, v39
	s_nop 0
	v_pk_mul_f32 v[36:37], v[32:33], v[38:39]
	v_pk_mul_f32 v[36:37], v[34:35], v[36:37]
	v_cvt_pk_bf16_f32 v224, v36, v37
	global_store_dword v2, v224, s[66:67]
	s_add_u32 s66, s66, 0x2c00
	s_addc_u32 s67, s67, 0
	s_waitcnt vmcnt(59)
	v_lshlrev_b32_e32 v28, 16, v166
	v_and_b32_e32 v29, 0xffff0000, v166
	v_lshlrev_b32_e32 v30, 16, v167
	v_and_b32_e32 v31, 0xffff0000, v167
	v_pk_fma_f32 v[32:33], v[4:5], v[20:21], v[16:17]
	v_pk_fma_f32 v[34:35], v[6:7], v[22:23], v[18:19]
	v_pk_fma_f32 v[32:33], v[8:9], v[24:25], v[32:33]
	v_pk_fma_f32 v[34:35], v[10:11], v[26:27], v[34:35]
	v_pk_fma_f32 v[32:33], v[12:13], v[28:29], v[32:33]
	v_pk_fma_f32 v[34:35], v[14:15], v[30:31], v[34:35]
	v_pk_mul_f32 v[36:37], v[32:33], s[58:59]
	v_pk_mul_f32 v[36:37], v[32:33], v[36:37]
	v_pk_fma_f32 v[36:37], v[32:33], v[36:37], v[32:33]
	v_pk_mul_f32 v[36:37], v[36:37], s[60:61]
	v_pk_mul_f32 v[36:37], v[36:37], s[68:69]
	v_exp_f32_e32 v38, v36
	v_exp_f32_e32 v39, v37
	s_nop 0
	v_pk_add_f32 v[38:39], v[38:39], s[82:83]
	v_rcp_f32_e32 v38, v38
	v_rcp_f32_e32 v39, v39
	s_nop 0
	v_pk_mul_f32 v[36:37], v[32:33], v[38:39]
	v_pk_mul_f32 v[36:37], v[34:35], v[36:37]
	v_cvt_pk_bf16_f32 v224, v36, v37
	global_store_dword v2, v224, s[66:67]
	s_add_u32 s66, s66, 0x2c00
	s_addc_u32 s67, s67, 0
	s_waitcnt vmcnt(58)
	v_lshlrev_b32_e32 v20, 16, v168
	v_and_b32_e32 v21, 0xffff0000, v168
	v_lshlrev_b32_e32 v22, 16, v169
	v_and_b32_e32 v23, 0xffff0000, v169
	v_pk_fma_f32 v[32:33], v[4:5], v[24:25], v[16:17]
	v_pk_fma_f32 v[34:35], v[6:7], v[26:27], v[18:19]
	v_pk_fma_f32 v[32:33], v[8:9], v[28:29], v[32:33]
	v_pk_fma_f32 v[34:35], v[10:11], v[30:31], v[34:35]
	v_pk_fma_f32 v[32:33], v[12:13], v[20:21], v[32:33]
	v_pk_fma_f32 v[34:35], v[14:15], v[22:23], v[34:35]
	v_pk_mul_f32 v[36:37], v[32:33], s[58:59]
	v_pk_mul_f32 v[36:37], v[32:33], v[36:37]
	v_pk_fma_f32 v[36:37], v[32:33], v[36:37], v[32:33]
	v_pk_mul_f32 v[36:37], v[36:37], s[60:61]
	v_pk_mul_f32 v[36:37], v[36:37], s[68:69]
	v_exp_f32_e32 v38, v36
	v_exp_f32_e32 v39, v37
	s_nop 0
	v_pk_add_f32 v[38:39], v[38:39], s[82:83]
	v_rcp_f32_e32 v38, v38
	v_rcp_f32_e32 v39, v39
	s_nop 0
	v_pk_mul_f32 v[36:37], v[32:33], v[38:39]
	v_pk_mul_f32 v[36:37], v[34:35], v[36:37]
	v_cvt_pk_bf16_f32 v224, v36, v37
	global_store_dword v2, v224, s[66:67]
	s_add_u32 s66, s66, 0x2c00
	s_addc_u32 s67, s67, 0
	s_waitcnt vmcnt(57)
; __device__ __forceinline__ float bf2f(unsigned b) { return __uint_as_float(b << 16); }
; __device__ __forceinline__ unsigned pk2(float lo, float hi) { unsigned r; asm("v_cvt_pk_bf16_f32 %0, %1, %2" : "=v"(r) : "v"(lo), "v"(hi)); return r; }
; __device__ __forceinline__ float gelu_t(float x) { return x * __builtin_amdgcn_rcpf(1.f + __expf(-1.5957691216057308f * (x + 0.044715f * x * x * x))); }
; __device__ __forceinline__ void act_item(int item, u16* UP, const u16* HALO, const float* sconv, const float* wconv, const float* bconv, float* out, int lane) {
;     ...
;         for (int t = 0; t < 16; ++t) {
;             const int row = rb * 64 + tb + t;
;             if (sample && (t & 3) == 0) { const int ns = (row - TP) >> 2; const float* s0 = sconv + (size_t)ns * 2 * FF2;
;                 const f32x2 a = *(const f32x2*)(s0 + j0), b = *(const f32x2*)(s0 + FF + j0), c = *(const f32x2*)(s0 + FF2 + j0), dd = *(const f32x2*)(s0 + FF2 + FF + j0);
;                 g2[0] = a.x; g2[1] = a.y; v2[0] = b.x; v2[1] = b.y; g1[0] = c.x; g1[1] = c.y; v1[0] = dd.x; v1[1] = dd.y; }
;             const float g0[2] = {bf2f(gw[t] & 0xffffu), bf2f(gw[t] >> 16)}, v0[2] = {bf2f(vw[t] & 0xffffu), bf2f(vw[t] >> 16)};
;             float res[2];
; #pragma unroll
;             for (int p = 0; p < 2; ++p) { const float cgv = bg[p] + wgt[0][p] * g2[p] + wgt[1][p] * g1[p] + wgt[2][p] * g0[p];
;                 const float cvv = bv[p] + wvl[0][p] * v2[p] + wvl[1][p] * v1[p] + wvl[2][p] * v0[p]; res[p] = gelu_t(cgv) * cvv;
;                 g2[p] = g1[p]; g1[p] = g0[p]; v2[p] = v1[p]; v1[p] = v0[p]; }
;             *(unsigned*)(UP + (size_t)row * FF2 + j0) = pk2(res[0], res[1]);
	v_lshlrev_b32_e32 v24, 16, v170
	v_and_b32_e32 v25, 0xffff0000, v170
	v_lshlrev_b32_e32 v26, 16, v171
	v_and_b32_e32 v27, 0xffff0000, v171
	v_pk_fma_f32 v[32:33], v[4:5], v[28:29], v[16:17]
	v_pk_fma_f32 v[34:35], v[6:7], v[30:31], v[18:19]
	v_pk_fma_f32 v[32:33], v[8:9], v[20:21], v[32:33]
	v_pk_fma_f32 v[34:35], v[10:11], v[22:23], v[34:35]
	v_pk_fma_f32 v[32:33], v[12:13], v[24:25], v[32:33]
	v_pk_fma_f32 v[34:35], v[14:15], v[26:27], v[34:35]
	v_pk_mul_f32 v[36:37], v[32:33], s[58:59]
	v_pk_mul_f32 v[36:37], v[32:33], v[36:37]
	v_pk_fma_f32 v[36:37], v[32:33], v[36:37], v[32:33]
	v_pk_mul_f32 v[36:37], v[36:37], s[60:61]
	v_pk_mul_f32 v[36:37], v[36:37], s[68:69]
	v_exp_f32_e32 v38, v36
	v_exp_f32_e32 v39, v37
	s_nop 0
	v_pk_add_f32 v[38:39], v[38:39], s[82:83]
	v_rcp_f32_e32 v38, v38
	v_rcp_f32_e32 v39, v39
	s_nop 0
	v_pk_mul_f32 v[36:37], v[32:33], v[38:39]
	v_pk_mul_f32 v[36:37], v[34:35], v[36:37]
	v_cvt_pk_bf16_f32 v224, v36, v37
	global_store_dword v2, v224, s[66:67]
	s_add_u32 s66, s66, 0x2c00
	s_addc_u32 s67, s67, 0
	s_waitcnt vmcnt(56)
	v_lshlrev_b32_e32 v28, 16, v172
	v_and_b32_e32 v29, 0xffff0000, v172
	v_lshlrev_b32_e32 v30, 16, v173
	v_and_b32_e32 v31, 0xffff0000, v173
	v_pk_fma_f32 v[32:33], v[4:5], v[20:21], v[16:17]
	v_pk_fma_f32 v[34:35], v[6:7], v[22:23], v[18:19]
	v_pk_fma_f32 v[32:33], v[8:9], v[24:25], v[32:33]
	v_pk_fma_f32 v[34:35], v[10:11], v[26:27], v[34:35]
	v_pk_fma_f32 v[32:33], v[12:13], v[28:29], v[32:33]
	v_pk_fma_f32 v[34:35], v[14:15], v[30:31], v[34:35]
	v_pk_mul_f32 v[36:37], v[32:33], s[58:59]
	v_pk_mul_f32 v[36:37], v[32:33], v[36:37]
	v_pk_fma_f32 v[36:37], v[32:33], v[36:37], v[32:33]
	v_pk_mul_f32 v[36:37], v[36:37], s[60:61]
	v_pk_mul_f32 v[36:37], v[36:37], s[68:69]
	v_exp_f32_e32 v38, v36
	v_exp_f32_e32 v39, v37
	s_nop 0
	v_pk_add_f32 v[38:39], v[38:39], s[82:83]
	v_rcp_f32_e32 v38, v38
	v_rcp_f32_e32 v39, v39
	s_nop 0
	v_pk_mul_f32 v[36:37], v[32:33], v[38:39]
	v_pk_mul_f32 v[36:37], v[34:35], v[36:37]
	v_cvt_pk_bf16_f32 v224, v36, v37
	global_store_dword v2, v224, s[66:67]
	s_add_u32 s66, s66, 0x2c00
	s_addc_u32 s67, s67, 0
	s_waitcnt vmcnt(55)
	v_lshlrev_b32_e32 v20, 16, v174
	v_and_b32_e32 v21, 0xffff0000, v174
	v_lshlrev_b32_e32 v22, 16, v175
	v_and_b32_e32 v23, 0xffff0000, v175
	v_pk_fma_f32 v[32:33], v[4:5], v[24:25], v[16:17]
	v_pk_fma_f32 v[34:35], v[6:7], v[26:27], v[18:19]
	v_pk_fma_f32 v[32:33], v[8:9], v[28:29], v[32:33]
	v_pk_fma_f32 v[34:35], v[10:11], v[30:31], v[34:35]
	v_pk_fma_f32 v[32:33], v[12:13], v[20:21], v[32:33]
	v_pk_fma_f32 v[34:35], v[14:15], v[22:23], v[34:35]
	v_pk_mul_f32 v[36:37], v[32:33], s[58:59]
	v_pk_mul_f32 v[36:37], v[32:33], v[36:37]
	v_pk_fma_f32 v[36:37], v[32:33], v[36:37], v[32:33]
	v_pk_mul_f32 v[36:37], v[36:37], s[60:61]
	v_pk_mul_f32 v[36:37], v[36:37], s[68:69]
	v_exp_f32_e32 v38, v36
	v_exp_f32_e32 v39, v37
	s_nop 0
	v_pk_add_f32 v[38:39], v[38:39], s[82:83]
	v_rcp_f32_e32 v38, v38
	v_rcp_f32_e32 v39, v39
	s_nop 0
	v_pk_mul_f32 v[36:37], v[32:33], v[38:39]
	v_pk_mul_f32 v[36:37], v[34:35], v[36:37]
	v_cvt_pk_bf16_f32 v224, v36, v37
	global_store_dword v2, v224, s[66:67]
	s_add_u32 s66, s66, 0x2c00
	s_addc_u32 s67, s67, 0
	s_waitcnt vmcnt(54)
	v_lshlrev_b32_e32 v24, 16, v176
	v_and_b32_e32 v25, 0xffff0000, v176
	v_lshlrev_b32_e32 v26, 16, v177
	v_and_b32_e32 v27, 0xffff0000, v177
	v_pk_fma_f32 v[32:33], v[4:5], v[28:29], v[16:17]
	v_pk_fma_f32 v[34:35], v[6:7], v[30:31], v[18:19]
	v_pk_fma_f32 v[32:33], v[8:9], v[20:21], v[32:33]
	v_pk_fma_f32 v[34:35], v[10:11], v[22:23], v[34:35]
	v_pk_fma_f32 v[32:33], v[12:13], v[24:25], v[32:33]
	v_pk_fma_f32 v[34:35], v[14:15], v[26:27], v[34:35]
	v_pk_mul_f32 v[36:37], v[32:33], s[58:59]
	v_pk_mul_f32 v[36:37], v[32:33], v[36:37]
	v_pk_fma_f32 v[36:37], v[32:33], v[36:37], v[32:33]
	v_pk_mul_f32 v[36:37], v[36:37], s[60:61]
	v_pk_mul_f32 v[36:37], v[36:37], s[68:69]
	v_exp_f32_e32 v38, v36
	v_exp_f32_e32 v39, v37
	s_nop 0
	v_pk_add_f32 v[38:39], v[38:39], s[82:83]
	v_rcp_f32_e32 v38, v38
	v_rcp_f32_e32 v39, v39
	s_nop 0
	v_pk_mul_f32 v[36:37], v[32:33], v[38:39]
	v_pk_mul_f32 v[36:37], v[34:35], v[36:37]
	v_cvt_pk_bf16_f32 v224, v36, v37
	global_store_dword v2, v224, s[66:67]
	s_add_u32 s66, s66, 0x2c00
	s_addc_u32 s67, s67, 0
	s_waitcnt vmcnt(53)
	v_lshlrev_b32_e32 v28, 16, v178
	v_and_b32_e32 v29, 0xffff0000, v178
	v_lshlrev_b32_e32 v30, 16, v179
	v_and_b32_e32 v31, 0xffff0000, v179
	v_pk_fma_f32 v[32:33], v[4:5], v[20:21], v[16:17]
	v_pk_fma_f32 v[34:35], v[6:7], v[22:23], v[18:19]
	v_pk_fma_f32 v[32:33], v[8:9], v[24:25], v[32:33]
	v_pk_fma_f32 v[34:35], v[10:11], v[26:27], v[34:35]
	v_pk_fma_f32 v[32:33], v[12:13], v[28:29], v[32:33]
	v_pk_fma_f32 v[34:35], v[14:15], v[30:31], v[34:35]
	v_pk_mul_f32 v[36:37], v[32:33], s[58:59]
	v_pk_mul_f32 v[36:37], v[32:33], v[36:37]
	v_pk_fma_f32 v[36:37], v[32:33], v[36:37], v[32:33]
	v_pk_mul_f32 v[36:37], v[36:37], s[60:61]
	v_pk_mul_f32 v[36:37], v[36:37], s[68:69]
	v_exp_f32_e32 v38, v36
	v_exp_f32_e32 v39, v37
	s_nop 0
	v_pk_add_f32 v[38:39], v[38:39], s[82:83]
	v_rcp_f32_e32 v38, v38
	v_rcp_f32_e32 v39, v39
	s_nop 0
	v_pk_mul_f32 v[36:37], v[32:33], v[38:39]
	v_pk_mul_f32 v[36:37], v[34:35], v[36:37]
	v_cvt_pk_bf16_f32 v224, v36, v37
	global_store_dword v2, v224, s[66:67]
	s_add_u32 s66, s66, 0x2c00
	s_addc_u32 s67, s67, 0
	s_waitcnt vmcnt(52)
; __device__ __forceinline__ float bf2f(unsigned b) { return __uint_as_float(b << 16); }
; __device__ __forceinline__ unsigned pk2(float lo, float hi) { unsigned r; asm("v_cvt_pk_bf16_f32 %0, %1, %2" : "=v"(r) : "v"(lo), "v"(hi)); return r; }
; __device__ __forceinline__ float gelu_t(float x) { return x * __builtin_amdgcn_rcpf(1.f + __expf(-1.5957691216057308f * (x + 0.044715f * x * x * x))); }
; __device__ __forceinline__ void act_item(int item, u16* UP, const u16* HALO, const float* sconv, const float* wconv, const float* bconv, float* out, int lane) {
;     ...
;         for (int t = 0; t < 16; ++t) {
;             const int row = rb * 64 + tb + t;
;             if (sample && (t & 3) == 0) { const int ns = (row - TP) >> 2; const float* s0 = sconv + (size_t)ns * 2 * FF2;
;                 const f32x2 a = *(const f32x2*)(s0 + j0), b = *(const f32x2*)(s0 + FF + j0), c = *(const f32x2*)(s0 + FF2 + j0), dd = *(const f32x2*)(s0 + FF2 + FF + j0);
;                 g2[0] = a.x; g2[1] = a.y; v2[0] = b.x; v2[1] = b.y; g1[0] = c.x; g1[1] = c.y; v1[0] = dd.x; v1[1] = dd.y; }
;             const float g0[2] = {bf2f(gw[t] & 0xffffu), bf2f(gw[t] >> 16)}, v0[2] = {bf2f(vw[t] & 0xffffu), bf2f(vw[t] >> 16)};
;             float res[2];
; #pragma unroll
;             for (int p = 0; p < 2; ++p) { const float cgv = bg[p] + wgt[0][p] * g2[p] + wgt[1][p] * g1[p] + wgt[2][p] * g0[p];
;                 const float cvv = bv[p] + wvl[0][p] * v2[p] + wvl[1][p] * v1[p] + wvl[2][p] * v0[p]; res[p] = gelu_t(cgv) * cvv;
;                 g2[p] = g1[p]; g1[p] = g0[p]; v2[p] = v1[p]; v1[p] = v0[p]; }
;             *(unsigned*)(UP + (size_t)row * FF2 + j0) = pk2(res[0], res[1]);
	v_lshlrev_b32_e32 v20, 16, v180
	v_and_b32_e32 v21, 0xffff0000, v180
	v_lshlrev_b32_e32 v22, 16, v181
	v_and_b32_e32 v23, 0xffff0000, v181
	v_pk_fma_f32 v[32:33], v[4:5], v[24:25], v[16:17]
	v_pk_fma_f32 v[34:35], v[6:7], v[26:27], v[18:19]
	v_pk_fma_f32 v[32:33], v[8:9], v[28:29], v[32:33]
	v_pk_fma_f32 v[34:35], v[10:11], v[30:31], v[34:35]
	v_pk_fma_f32 v[32:33], v[12:13], v[20:21], v[32:33]
	v_pk_fma_f32 v[34:35], v[14:15], v[22:23], v[34:35]
	v_pk_mul_f32 v[36:37], v[32:33], s[58:59]
	v_pk_mul_f32 v[36:37], v[32:33], v[36:37]
	v_pk_fma_f32 v[36:37], v[32:33], v[36:37], v[32:33]
	v_pk_mul_f32 v[36:37], v[36:37], s[60:61]
	v_pk_mul_f32 v[36:37], v[36:37], s[68:69]
	v_exp_f32_e32 v38, v36
	v_exp_f32_e32 v39, v37
	s_nop 0
	v_pk_add_f32 v[38:39], v[38:39], s[82:83]
	v_rcp_f32_e32 v38, v38
	v_rcp_f32_e32 v39, v39
	s_nop 0
	v_pk_mul_f32 v[36:37], v[32:33], v[38:39]
	v_pk_mul_f32 v[36:37], v[34:35], v[36:37]
	v_cvt_pk_bf16_f32 v224, v36, v37
	global_store_dword v2, v224, s[66:67]
	s_add_u32 s66, s66, 0x2c00
	s_addc_u32 s67, s67, 0
	s_waitcnt vmcnt(51)
	v_lshlrev_b32_e32 v24, 16, v182
	v_and_b32_e32 v25, 0xffff0000, v182
	v_lshlrev_b32_e32 v26, 16, v183
	v_and_b32_e32 v27, 0xffff0000, v183
	v_pk_fma_f32 v[32:33], v[4:5], v[28:29], v[16:17]
	v_pk_fma_f32 v[34:35], v[6:7], v[30:31], v[18:19]
	v_pk_fma_f32 v[32:33], v[8:9], v[20:21], v[32:33]
	v_pk_fma_f32 v[34:35], v[10:11], v[22:23], v[34:35]
	v_pk_fma_f32 v[32:33], v[12:13], v[24:25], v[32:33]
	v_pk_fma_f32 v[34:35], v[14:15], v[26:27], v[34:35]
	v_pk_mul_f32 v[36:37], v[32:33], s[58:59]
	v_pk_mul_f32 v[36:37], v[32:33], v[36:37]
	v_pk_fma_f32 v[36:37], v[32:33], v[36:37], v[32:33]
	v_pk_mul_f32 v[36:37], v[36:37], s[60:61]
	v_pk_mul_f32 v[36:37], v[36:37], s[68:69]
	v_exp_f32_e32 v38, v36
	v_exp_f32_e32 v39, v37
	s_nop 0
	v_pk_add_f32 v[38:39], v[38:39], s[82:83]
	v_rcp_f32_e32 v38, v38
	v_rcp_f32_e32 v39, v39
	s_nop 0
	v_pk_mul_f32 v[36:37], v[32:33], v[38:39]
	v_pk_mul_f32 v[36:37], v[34:35], v[36:37]
	v_cvt_pk_bf16_f32 v224, v36, v37
	global_store_dword v2, v224, s[66:67]
	s_add_u32 s66, s66, 0x2c00
	s_addc_u32 s67, s67, 0
	s_waitcnt vmcnt(50)
	v_lshlrev_b32_e32 v28, 16, v184
	v_and_b32_e32 v29, 0xffff0000, v184
	v_lshlrev_b32_e32 v30, 16, v185
	v_and_b32_e32 v31, 0xffff0000, v185
	v_pk_fma_f32 v[32:33], v[4:5], v[20:21], v[16:17]
	v_pk_fma_f32 v[34:35], v[6:7], v[22:23], v[18:19]
	v_pk_fma_f32 v[32:33], v[8:9], v[24:25], v[32:33]
	v_pk_fma_f32 v[34:35], v[10:11], v[26:27], v[34:35]
	v_pk_fma_f32 v[32:33], v[12:13], v[28:29], v[32:33]
	v_pk_fma_f32 v[34:35], v[14:15], v[30:31], v[34:35]
	v_pk_mul_f32 v[36:37], v[32:33], s[58:59]
	v_pk_mul_f32 v[36:37], v[32:33], v[36:37]
	v_pk_fma_f32 v[36:37], v[32:33], v[36:37], v[32:33]
	v_pk_mul_f32 v[36:37], v[36:37], s[60:61]
	v_pk_mul_f32 v[36:37], v[36:37], s[68:69]
	v_exp_f32_e32 v38, v36
	v_exp_f32_e32 v39, v37
	s_nop 0
	v_pk_add_f32 v[38:39], v[38:39], s[82:83]
	v_rcp_f32_e32 v38, v38
	v_rcp_f32_e32 v39, v39
	s_nop 0
	v_pk_mul_f32 v[36:37], v[32:33], v[38:39]
	v_pk_mul_f32 v[36:37], v[34:35], v[36:37]
	v_cvt_pk_bf16_f32 v224, v36, v37
	global_store_dword v2, v224, s[66:67]
	s_add_u32 s66, s66, 0x2c00
	s_addc_u32 s67, s67, 0
	s_waitcnt vmcnt(49)
	v_lshlrev_b32_e32 v20, 16, v186
	v_and_b32_e32 v21, 0xffff0000, v186
	v_lshlrev_b32_e32 v22, 16, v187
	v_and_b32_e32 v23, 0xffff0000, v187
	v_pk_fma_f32 v[32:33], v[4:5], v[24:25], v[16:17]
	v_pk_fma_f32 v[34:35], v[6:7], v[26:27], v[18:19]
	v_pk_fma_f32 v[32:33], v[8:9], v[28:29], v[32:33]
	v_pk_fma_f32 v[34:35], v[10:11], v[30:31], v[34:35]
	v_pk_fma_f32 v[32:33], v[12:13], v[20:21], v[32:33]
	v_pk_fma_f32 v[34:35], v[14:15], v[22:23], v[34:35]
	v_pk_mul_f32 v[36:37], v[32:33], s[58:59]
	v_pk_mul_f32 v[36:37], v[32:33], v[36:37]
	v_pk_fma_f32 v[36:37], v[32:33], v[36:37], v[32:33]
	v_pk_mul_f32 v[36:37], v[36:37], s[60:61]
	v_pk_mul_f32 v[36:37], v[36:37], s[68:69]
	v_exp_f32_e32 v38, v36
	v_exp_f32_e32 v39, v37
	s_nop 0
	v_pk_add_f32 v[38:39], v[38:39], s[82:83]
	v_rcp_f32_e32 v38, v38
	v_rcp_f32_e32 v39, v39
	s_nop 0
	v_pk_mul_f32 v[36:37], v[32:33], v[38:39]
	v_pk_mul_f32 v[36:37], v[34:35], v[36:37]
	v_cvt_pk_bf16_f32 v224, v36, v37
	global_store_dword v2, v224, s[66:67]
	s_add_u32 s66, s66, 0x2c00
	s_addc_u32 s67, s67, 0
	s_waitcnt vmcnt(48)
	v_lshlrev_b32_e32 v24, 16, v188
	v_and_b32_e32 v25, 0xffff0000, v188
	v_lshlrev_b32_e32 v26, 16, v189
	v_and_b32_e32 v27, 0xffff0000, v189
	v_pk_fma_f32 v[32:33], v[4:5], v[28:29], v[16:17]
	v_pk_fma_f32 v[34:35], v[6:7], v[30:31], v[18:19]
	v_pk_fma_f32 v[32:33], v[8:9], v[20:21], v[32:33]
	v_pk_fma_f32 v[34:35], v[10:11], v[22:23], v[34:35]
	v_pk_fma_f32 v[32:33], v[12:13], v[24:25], v[32:33]
	v_pk_fma_f32 v[34:35], v[14:15], v[26:27], v[34:35]
	v_pk_mul_f32 v[36:37], v[32:33], s[58:59]
	v_pk_mul_f32 v[36:37], v[32:33], v[36:37]
	v_pk_fma_f32 v[36:37], v[32:33], v[36:37], v[32:33]
	v_pk_mul_f32 v[36:37], v[36:37], s[60:61]
	v_pk_mul_f32 v[36:37], v[36:37], s[68:69]
	v_exp_f32_e32 v38, v36
	v_exp_f32_e32 v39, v37
	s_nop 0
	v_pk_add_f32 v[38:39], v[38:39], s[82:83]
	v_rcp_f32_e32 v38, v38
	v_rcp_f32_e32 v39, v39
	s_nop 0
	v_pk_mul_f32 v[36:37], v[32:33], v[38:39]
	v_pk_mul_f32 v[36:37], v[34:35], v[36:37]
	v_cvt_pk_bf16_f32 v224, v36, v37
	global_store_dword v2, v224, s[66:67]
	s_add_u32 s66, s66, 0x2c00
	s_addc_u32 s67, s67, 0
	s_waitcnt vmcnt(47)
; __device__ __forceinline__ float bf2f(unsigned b) { return __uint_as_float(b << 16); }
; __device__ __forceinline__ unsigned pk2(float lo, float hi) { unsigned r; asm("v_cvt_pk_bf16_f32 %0, %1, %2" : "=v"(r) : "v"(lo), "v"(hi)); return r; }
; __device__ __forceinline__ float gelu_t(float x) { return x * __builtin_amdgcn_rcpf(1.f + __expf(-1.5957691216057308f * (x + 0.044715f * x * x * x))); }
; __device__ __forceinline__ void act_item(int item, u16* UP, const u16* HALO, const float* sconv, const float* wconv, const float* bconv, float* out, int lane) {
;     ...
;         for (int t = 0; t < 16; ++t) {
;             const int row = rb * 64 + tb + t;
;             if (sample && (t & 3) == 0) { const int ns = (row - TP) >> 2; const float* s0 = sconv + (size_t)ns * 2 * FF2;
;                 const f32x2 a = *(const f32x2*)(s0 + j0), b = *(const f32x2*)(s0 + FF + j0), c = *(const f32x2*)(s0 + FF2 + j0), dd = *(const f32x2*)(s0 + FF2 + FF + j0);
;                 g2[0] = a.x; g2[1] = a.y; v2[0] = b.x; v2[1] = b.y; g1[0] = c.x; g1[1] = c.y; v1[0] = dd.x; v1[1] = dd.y; }
;             const float g0[2] = {bf2f(gw[t] & 0xffffu), bf2f(gw[t] >> 16)}, v0[2] = {bf2f(vw[t] & 0xffffu), bf2f(vw[t] >> 16)};
;             float res[2];
; #pragma unroll
;             for (int p = 0; p < 2; ++p) { const float cgv = bg[p] + wgt[0][p] * g2[p] + wgt[1][p] * g1[p] + wgt[2][p] * g0[p];
;                 const float cvv = bv[p] + wvl[0][p] * v2[p] + wvl[1][p] * v1[p] + wvl[2][p] * v0[p]; res[p] = gelu_t(cgv) * cvv;
;                 g2[p] = g1[p]; g1[p] = g0[p]; v2[p] = v1[p]; v1[p] = v0[p]; }
;             *(unsigned*)(UP + (size_t)row * FF2 + j0) = pk2(res[0], res[1]);
	v_lshlrev_b32_e32 v28, 16, v190
	v_and_b32_e32 v29, 0xffff0000, v190
	v_lshlrev_b32_e32 v30, 16, v191
	v_and_b32_e32 v31, 0xffff0000, v191
	v_pk_fma_f32 v[32:33], v[4:5], v[20:21], v[16:17]
	v_pk_fma_f32 v[34:35], v[6:7], v[22:23], v[18:19]
	v_pk_fma_f32 v[32:33], v[8:9], v[24:25], v[32:33]
	v_pk_fma_f32 v[34:35], v[10:11], v[26:27], v[34:35]
	v_pk_fma_f32 v[32:33], v[12:13], v[28:29], v[32:33]
	v_pk_fma_f32 v[34:35], v[14:15], v[30:31], v[34:35]
	v_pk_mul_f32 v[36:37], v[32:33], s[58:59]
	v_pk_mul_f32 v[36:37], v[32:33], v[36:37]
	v_pk_fma_f32 v[36:37], v[32:33], v[36:37], v[32:33]
	v_pk_mul_f32 v[36:37], v[36:37], s[60:61]
	v_pk_mul_f32 v[36:37], v[36:37], s[68:69]
	v_exp_f32_e32 v38, v36
	v_exp_f32_e32 v39, v37
	s_nop 0
	v_pk_add_f32 v[38:39], v[38:39], s[82:83]
	v_rcp_f32_e32 v38, v38
	v_rcp_f32_e32 v39, v39
	s_nop 0
	v_pk_mul_f32 v[36:37], v[32:33], v[38:39]
	v_pk_mul_f32 v[36:37], v[34:35], v[36:37]
	v_cvt_pk_bf16_f32 v224, v36, v37
	global_store_dword v2, v224, s[66:67]
	s_add_u32 s66, s66, 0x2c00
	s_addc_u32 s67, s67, 0
	s_waitcnt vmcnt(30)
	v_lshlrev_b32_e32 v20, 16, v192
	v_and_b32_e32 v21, 0xffff0000, v192
	v_lshlrev_b32_e32 v22, 16, v193
	v_and_b32_e32 v23, 0xffff0000, v193
	v_pk_fma_f32 v[32:33], v[4:5], v[24:25], v[16:17]
	v_pk_fma_f32 v[34:35], v[6:7], v[26:27], v[18:19]
	v_pk_fma_f32 v[32:33], v[8:9], v[28:29], v[32:33]
	v_pk_fma_f32 v[34:35], v[10:11], v[30:31], v[34:35]
	v_pk_fma_f32 v[32:33], v[12:13], v[20:21], v[32:33]
	v_pk_fma_f32 v[34:35], v[14:15], v[22:23], v[34:35]
	v_pk_mul_f32 v[36:37], v[32:33], s[58:59]
	v_pk_mul_f32 v[36:37], v[32:33], v[36:37]
	v_pk_fma_f32 v[36:37], v[32:33], v[36:37], v[32:33]
	v_pk_mul_f32 v[36:37], v[36:37], s[60:61]
	v_pk_mul_f32 v[36:37], v[36:37], s[68:69]
	v_exp_f32_e32 v38, v36
	v_exp_f32_e32 v39, v37
	s_nop 0
	v_pk_add_f32 v[38:39], v[38:39], s[82:83]
	v_rcp_f32_e32 v38, v38
	v_rcp_f32_e32 v39, v39
	s_nop 0
	v_pk_mul_f32 v[36:37], v[32:33], v[38:39]
	v_pk_mul_f32 v[36:37], v[34:35], v[36:37]
	v_cvt_pk_bf16_f32 v224, v36, v37
	global_store_dword v2, v224, s[66:67]
	s_add_u32 s66, s66, 0x2c00
	s_addc_u32 s67, s67, 0
	s_waitcnt vmcnt(29)
	v_lshlrev_b32_e32 v24, 16, v194
	v_and_b32_e32 v25, 0xffff0000, v194
	v_lshlrev_b32_e32 v26, 16, v195
	v_and_b32_e32 v27, 0xffff0000, v195
	v_pk_fma_f32 v[32:33], v[4:5], v[28:29], v[16:17]
	v_pk_fma_f32 v[34:35], v[6:7], v[30:31], v[18:19]
	v_pk_fma_f32 v[32:33], v[8:9], v[20:21], v[32:33]
	v_pk_fma_f32 v[34:35], v[10:11], v[22:23], v[34:35]
	v_pk_fma_f32 v[32:33], v[12:13], v[24:25], v[32:33]
	v_pk_fma_f32 v[34:35], v[14:15], v[26:27], v[34:35]
	v_pk_mul_f32 v[36:37], v[32:33], s[58:59]
	v_pk_mul_f32 v[36:37], v[32:33], v[36:37]
	v_pk_fma_f32 v[36:37], v[32:33], v[36:37], v[32:33]
	v_pk_mul_f32 v[36:37], v[36:37], s[60:61]
	v_pk_mul_f32 v[36:37], v[36:37], s[68:69]
	v_exp_f32_e32 v38, v36
	v_exp_f32_e32 v39, v37
	s_nop 0
	v_pk_add_f32 v[38:39], v[38:39], s[82:83]
	v_rcp_f32_e32 v38, v38
	v_rcp_f32_e32 v39, v39
	s_nop 0
	v_pk_mul_f32 v[36:37], v[32:33], v[38:39]
	v_pk_mul_f32 v[36:37], v[34:35], v[36:37]
	v_cvt_pk_bf16_f32 v224, v36, v37
	global_store_dword v2, v224, s[66:67]
	s_add_u32 s66, s66, 0x2c00
	s_addc_u32 s67, s67, 0
	s_waitcnt vmcnt(28)
	v_lshlrev_b32_e32 v28, 16, v196
	v_and_b32_e32 v29, 0xffff0000, v196
	v_lshlrev_b32_e32 v30, 16, v197
	v_and_b32_e32 v31, 0xffff0000, v197
	v_pk_fma_f32 v[32:33], v[4:5], v[20:21], v[16:17]
	v_pk_fma_f32 v[34:35], v[6:7], v[22:23], v[18:19]
	v_pk_fma_f32 v[32:33], v[8:9], v[24:25], v[32:33]
	v_pk_fma_f32 v[34:35], v[10:11], v[26:27], v[34:35]
	v_pk_fma_f32 v[32:33], v[12:13], v[28:29], v[32:33]
	v_pk_fma_f32 v[34:35], v[14:15], v[30:31], v[34:35]
	v_pk_mul_f32 v[36:37], v[32:33], s[58:59]
	v_pk_mul_f32 v[36:37], v[32:33], v[36:37]
	v_pk_fma_f32 v[36:37], v[32:33], v[36:37], v[32:33]
	v_pk_mul_f32 v[36:37], v[36:37], s[60:61]
	v_pk_mul_f32 v[36:37], v[36:37], s[68:69]
	v_exp_f32_e32 v38, v36
	v_exp_f32_e32 v39, v37
	s_nop 0
	v_pk_add_f32 v[38:39], v[38:39], s[82:83]
	v_rcp_f32_e32 v38, v38
	v_rcp_f32_e32 v39, v39
	s_nop 0
	v_pk_mul_f32 v[36:37], v[32:33], v[38:39]
	v_pk_mul_f32 v[36:37], v[34:35], v[36:37]
	v_cvt_pk_bf16_f32 v224, v36, v37
	global_store_dword v2, v224, s[66:67]
	s_add_u32 s66, s66, 0x2c00
	s_addc_u32 s67, s67, 0
	s_waitcnt vmcnt(27)
	v_lshlrev_b32_e32 v20, 16, v198
	v_and_b32_e32 v21, 0xffff0000, v198
	v_lshlrev_b32_e32 v22, 16, v199
	v_and_b32_e32 v23, 0xffff0000, v199
	v_pk_fma_f32 v[32:33], v[4:5], v[24:25], v[16:17]
	v_pk_fma_f32 v[34:35], v[6:7], v[26:27], v[18:19]
	v_pk_fma_f32 v[32:33], v[8:9], v[28:29], v[32:33]
	v_pk_fma_f32 v[34:35], v[10:11], v[30:31], v[34:35]
	v_pk_fma_f32 v[32:33], v[12:13], v[20:21], v[32:33]
	v_pk_fma_f32 v[34:35], v[14:15], v[22:23], v[34:35]
	v_pk_mul_f32 v[36:37], v[32:33], s[58:59]
	v_pk_mul_f32 v[36:37], v[32:33], v[36:37]
	v_pk_fma_f32 v[36:37], v[32:33], v[36:37], v[32:33]
	v_pk_mul_f32 v[36:37], v[36:37], s[60:61]
	v_pk_mul_f32 v[36:37], v[36:37], s[68:69]
	v_exp_f32_e32 v38, v36
	v_exp_f32_e32 v39, v37
	s_nop 0
	v_pk_add_f32 v[38:39], v[38:39], s[82:83]
	v_rcp_f32_e32 v38, v38
	v_rcp_f32_e32 v39, v39
	s_nop 0
	v_pk_mul_f32 v[36:37], v[32:33], v[38:39]
	v_pk_mul_f32 v[36:37], v[34:35], v[36:37]
	v_cvt_pk_bf16_f32 v224, v36, v37
	global_store_dword v2, v224, s[66:67]
	s_add_u32 s66, s66, 0x2c00
	s_addc_u32 s67, s67, 0
	s_waitcnt vmcnt(26)
; __device__ __forceinline__ float bf2f(unsigned b) { return __uint_as_float(b << 16); }
; __device__ __forceinline__ unsigned pk2(float lo, float hi) { unsigned r; asm("v_cvt_pk_bf16_f32 %0, %1, %2" : "=v"(r) : "v"(lo), "v"(hi)); return r; }
; __device__ __forceinline__ float gelu_t(float x) { return x * __builtin_amdgcn_rcpf(1.f + __expf(-1.5957691216057308f * (x + 0.044715f * x * x * x))); }
; __device__ __forceinline__ void act_item(int item, u16* UP, const u16* HALO, const float* sconv, const float* wconv, const float* bconv, float* out, int lane) {
;     ...
;         for (int t = 0; t < 16; ++t) {
;             const int row = rb * 64 + tb + t;
;             if (sample && (t & 3) == 0) { const int ns = (row - TP) >> 2; const float* s0 = sconv + (size_t)ns * 2 * FF2;
;                 const f32x2 a = *(const f32x2*)(s0 + j0), b = *(const f32x2*)(s0 + FF + j0), c = *(const f32x2*)(s0 + FF2 + j0), dd = *(const f32x2*)(s0 + FF2 + FF + j0);
;                 g2[0] = a.x; g2[1] = a.y; v2[0] = b.x; v2[1] = b.y; g1[0] = c.x; g1[1] = c.y; v1[0] = dd.x; v1[1] = dd.y; }
;             const float g0[2] = {bf2f(gw[t] & 0xffffu), bf2f(gw[t] >> 16)}, v0[2] = {bf2f(vw[t] & 0xffffu), bf2f(vw[t] >> 16)};
;             float res[2];
; #pragma unroll
;             for (int p = 0; p < 2; ++p) { const float cgv = bg[p] + wgt[0][p] * g2[p] + wgt[1][p] * g1[p] + wgt[2][p] * g0[p];
;                 const float cvv = bv[p] + wvl[0][p] * v2[p] + wvl[1][p] * v1[p] + wvl[2][p] * v0[p]; res[p] = gelu_t(cgv) * cvv;
;                 g2[p] = g1[p]; g1[p] = g0[p]; v2[p] = v1[p]; v1[p] = v0[p]; }
;             *(unsigned*)(UP + (size_t)row * FF2 + j0) = pk2(res[0], res[1]);
	v_lshlrev_b32_e32 v24, 16, v200
	v_and_b32_e32 v25, 0xffff0000, v200
	v_lshlrev_b32_e32 v26, 16, v201
	v_and_b32_e32 v27, 0xffff0000, v201
	v_pk_fma_f32 v[32:33], v[4:5], v[28:29], v[16:17]
	v_pk_fma_f32 v[34:35], v[6:7], v[30:31], v[18:19]
	v_pk_fma_f32 v[32:33], v[8:9], v[20:21], v[32:33]
	v_pk_fma_f32 v[34:35], v[10:11], v[22:23], v[34:35]
	v_pk_fma_f32 v[32:33], v[12:13], v[24:25], v[32:33]
	v_pk_fma_f32 v[34:35], v[14:15], v[26:27], v[34:35]
	v_pk_mul_f32 v[36:37], v[32:33], s[58:59]
	v_pk_mul_f32 v[36:37], v[32:33], v[36:37]
	v_pk_fma_f32 v[36:37], v[32:33], v[36:37], v[32:33]
	v_pk_mul_f32 v[36:37], v[36:37], s[60:61]
	v_pk_mul_f32 v[36:37], v[36:37], s[68:69]
	v_exp_f32_e32 v38, v36
	v_exp_f32_e32 v39, v37
	s_nop 0
	v_pk_add_f32 v[38:39], v[38:39], s[82:83]
	v_rcp_f32_e32 v38, v38
	v_rcp_f32_e32 v39, v39
	s_nop 0
	v_pk_mul_f32 v[36:37], v[32:33], v[38:39]
	v_pk_mul_f32 v[36:37], v[34:35], v[36:37]
	v_cvt_pk_bf16_f32 v224, v36, v37
	global_store_dword v2, v224, s[66:67]
	s_add_u32 s66, s66, 0x2c00
	s_addc_u32 s67, s67, 0
	s_waitcnt vmcnt(25)
	v_lshlrev_b32_e32 v28, 16, v202
	v_and_b32_e32 v29, 0xffff0000, v202
	v_lshlrev_b32_e32 v30, 16, v203
	v_and_b32_e32 v31, 0xffff0000, v203
	v_pk_fma_f32 v[32:33], v[4:5], v[20:21], v[16:17]
	v_pk_fma_f32 v[34:35], v[6:7], v[22:23], v[18:19]
	v_pk_fma_f32 v[32:33], v[8:9], v[24:25], v[32:33]
	v_pk_fma_f32 v[34:35], v[10:11], v[26:27], v[34:35]
	v_pk_fma_f32 v[32:33], v[12:13], v[28:29], v[32:33]
	v_pk_fma_f32 v[34:35], v[14:15], v[30:31], v[34:35]
	v_pk_mul_f32 v[36:37], v[32:33], s[58:59]
	v_pk_mul_f32 v[36:37], v[32:33], v[36:37]
	v_pk_fma_f32 v[36:37], v[32:33], v[36:37], v[32:33]
	v_pk_mul_f32 v[36:37], v[36:37], s[60:61]
	v_pk_mul_f32 v[36:37], v[36:37], s[68:69]
	v_exp_f32_e32 v38, v36
	v_exp_f32_e32 v39, v37
	s_nop 0
	v_pk_add_f32 v[38:39], v[38:39], s[82:83]
	v_rcp_f32_e32 v38, v38
	v_rcp_f32_e32 v39, v39
	s_nop 0
	v_pk_mul_f32 v[36:37], v[32:33], v[38:39]
	v_pk_mul_f32 v[36:37], v[34:35], v[36:37]
	v_cvt_pk_bf16_f32 v224, v36, v37
	global_store_dword v2, v224, s[66:67]
	s_add_u32 s66, s66, 0x2c00
	s_addc_u32 s67, s67, 0
	s_waitcnt vmcnt(24)
	v_lshlrev_b32_e32 v20, 16, v204
	v_and_b32_e32 v21, 0xffff0000, v204
	v_lshlrev_b32_e32 v22, 16, v205
	v_and_b32_e32 v23, 0xffff0000, v205
	v_pk_fma_f32 v[32:33], v[4:5], v[24:25], v[16:17]
	v_pk_fma_f32 v[34:35], v[6:7], v[26:27], v[18:19]
	v_pk_fma_f32 v[32:33], v[8:9], v[28:29], v[32:33]
	v_pk_fma_f32 v[34:35], v[10:11], v[30:31], v[34:35]
	v_pk_fma_f32 v[32:33], v[12:13], v[20:21], v[32:33]
	v_pk_fma_f32 v[34:35], v[14:15], v[22:23], v[34:35]
	v_pk_mul_f32 v[36:37], v[32:33], s[58:59]
	v_pk_mul_f32 v[36:37], v[32:33], v[36:37]
	v_pk_fma_f32 v[36:37], v[32:33], v[36:37], v[32:33]
	v_pk_mul_f32 v[36:37], v[36:37], s[60:61]
	v_pk_mul_f32 v[36:37], v[36:37], s[68:69]
	v_exp_f32_e32 v38, v36
	v_exp_f32_e32 v39, v37
	s_nop 0
	v_pk_add_f32 v[38:39], v[38:39], s[82:83]
	v_rcp_f32_e32 v38, v38
	v_rcp_f32_e32 v39, v39
	s_nop 0
	v_pk_mul_f32 v[36:37], v[32:33], v[38:39]
	v_pk_mul_f32 v[36:37], v[34:35], v[36:37]
	v_cvt_pk_bf16_f32 v224, v36, v37
	global_store_dword v2, v224, s[66:67]
	s_add_u32 s66, s66, 0x2c00
	s_addc_u32 s67, s67, 0
	s_waitcnt vmcnt(23)
	v_lshlrev_b32_e32 v24, 16, v206
	v_and_b32_e32 v25, 0xffff0000, v206
	v_lshlrev_b32_e32 v26, 16, v207
	v_and_b32_e32 v27, 0xffff0000, v207
	v_pk_fma_f32 v[32:33], v[4:5], v[28:29], v[16:17]
	v_pk_fma_f32 v[34:35], v[6:7], v[30:31], v[18:19]
	v_pk_fma_f32 v[32:33], v[8:9], v[20:21], v[32:33]
	v_pk_fma_f32 v[34:35], v[10:11], v[22:23], v[34:35]
	v_pk_fma_f32 v[32:33], v[12:13], v[24:25], v[32:33]
	v_pk_fma_f32 v[34:35], v[14:15], v[26:27], v[34:35]
	v_pk_mul_f32 v[36:37], v[32:33], s[58:59]
	v_pk_mul_f32 v[36:37], v[32:33], v[36:37]
	v_pk_fma_f32 v[36:37], v[32:33], v[36:37], v[32:33]
	v_pk_mul_f32 v[36:37], v[36:37], s[60:61]
	v_pk_mul_f32 v[36:37], v[36:37], s[68:69]
	v_exp_f32_e32 v38, v36
	v_exp_f32_e32 v39, v37
	s_nop 0
	v_pk_add_f32 v[38:39], v[38:39], s[82:83]
	v_rcp_f32_e32 v38, v38
	v_rcp_f32_e32 v39, v39
	s_nop 0
	v_pk_mul_f32 v[36:37], v[32:33], v[38:39]
	v_pk_mul_f32 v[36:37], v[34:35], v[36:37]
	v_cvt_pk_bf16_f32 v224, v36, v37
	global_store_dword v2, v224, s[66:67]
	s_add_u32 s66, s66, 0x2c00
	s_addc_u32 s67, s67, 0
	s_waitcnt vmcnt(22)
	v_lshlrev_b32_e32 v28, 16, v208
	v_and_b32_e32 v29, 0xffff0000, v208
	v_lshlrev_b32_e32 v30, 16, v209
	v_and_b32_e32 v31, 0xffff0000, v209
	v_pk_fma_f32 v[32:33], v[4:5], v[20:21], v[16:17]
	v_pk_fma_f32 v[34:35], v[6:7], v[22:23], v[18:19]
	v_pk_fma_f32 v[32:33], v[8:9], v[24:25], v[32:33]
	v_pk_fma_f32 v[34:35], v[10:11], v[26:27], v[34:35]
	v_pk_fma_f32 v[32:33], v[12:13], v[28:29], v[32:33]
	v_pk_fma_f32 v[34:35], v[14:15], v[30:31], v[34:35]
	v_pk_mul_f32 v[36:37], v[32:33], s[58:59]
	v_pk_mul_f32 v[36:37], v[32:33], v[36:37]
	v_pk_fma_f32 v[36:37], v[32:33], v[36:37], v[32:33]
	v_pk_mul_f32 v[36:37], v[36:37], s[60:61]
	v_pk_mul_f32 v[36:37], v[36:37], s[68:69]
	v_exp_f32_e32 v38, v36
	v_exp_f32_e32 v39, v37
	s_nop 0
	v_pk_add_f32 v[38:39], v[38:39], s[82:83]
	v_rcp_f32_e32 v38, v38
	v_rcp_f32_e32 v39, v39
	s_nop 0
	v_pk_mul_f32 v[36:37], v[32:33], v[38:39]
	v_pk_mul_f32 v[36:37], v[34:35], v[36:37]
	v_cvt_pk_bf16_f32 v224, v36, v37
	global_store_dword v2, v224, s[66:67]
	s_add_u32 s66, s66, 0x2c00
	s_addc_u32 s67, s67, 0
	s_waitcnt vmcnt(21)
; __device__ __forceinline__ float bf2f(unsigned b) { return __uint_as_float(b << 16); }
; __device__ __forceinline__ unsigned pk2(float lo, float hi) { unsigned r; asm("v_cvt_pk_bf16_f32 %0, %1, %2" : "=v"(r) : "v"(lo), "v"(hi)); return r; }
; __device__ __forceinline__ float gelu_t(float x) { return x * __builtin_amdgcn_rcpf(1.f + __expf(-1.5957691216057308f * (x + 0.044715f * x * x * x))); }
; __device__ __forceinline__ void act_item(int item, u16* UP, const u16* HALO, const float* sconv, const float* wconv, const float* bconv, float* out, int lane) {
;     ...
;         for (int t = 0; t < 16; ++t) {
;             const int row = rb * 64 + tb + t;
;             if (sample && (t & 3) == 0) { const int ns = (row - TP) >> 2; const float* s0 = sconv + (size_t)ns * 2 * FF2;
;                 const f32x2 a = *(const f32x2*)(s0 + j0), b = *(const f32x2*)(s0 + FF + j0), c = *(const f32x2*)(s0 + FF2 + j0), dd = *(const f32x2*)(s0 + FF2 + FF + j0);
;                 g2[0] = a.x; g2[1] = a.y; v2[0] = b.x; v2[1] = b.y; g1[0] = c.x; g1[1] = c.y; v1[0] = dd.x; v1[1] = dd.y; }
;             const float g0[2] = {bf2f(gw[t] & 0xffffu), bf2f(gw[t] >> 16)}, v0[2] = {bf2f(vw[t] & 0xffffu), bf2f(vw[t] >> 16)};
;             float res[2];
; #pragma unroll
;             for (int p = 0; p < 2; ++p) { const float cgv = bg[p] + wgt[0][p] * g2[p] + wgt[1][p] * g1[p] + wgt[2][p] * g0[p];
;                 const float cvv = bv[p] + wvl[0][p] * v2[p] + wvl[1][p] * v1[p] + wvl[2][p] * v0[p]; res[p] = gelu_t(cgv) * cvv;
;                 g2[p] = g1[p]; g1[p] = g0[p]; v2[p] = v1[p]; v1[p] = v0[p]; }
;             *(unsigned*)(UP + (size_t)row * FF2 + j0) = pk2(res[0], res[1]);
;             if (!sample) { const int tq = row & 2047; if (tq >= 2046) { float* o = out + O_CONVP + ((size_t)(row >> 11) * 2 + (tq - 2046)) * FF2;
;                     *(f32x2*)(o + j0) = (f32x2){g0[0], g0[1]}; *(f32x2*)(o + FF + j0) = (f32x2){v0[0], v0[1]}; } }
	v_lshlrev_b32_e32 v20, 16, v210
	v_and_b32_e32 v21, 0xffff0000, v210
	v_lshlrev_b32_e32 v22, 16, v211
	v_and_b32_e32 v23, 0xffff0000, v211
	v_pk_fma_f32 v[32:33], v[4:5], v[24:25], v[16:17]
	v_pk_fma_f32 v[34:35], v[6:7], v[26:27], v[18:19]
	v_pk_fma_f32 v[32:33], v[8:9], v[28:29], v[32:33]
	v_pk_fma_f32 v[34:35], v[10:11], v[30:31], v[34:35]
	v_pk_fma_f32 v[32:33], v[12:13], v[20:21], v[32:33]
	v_pk_fma_f32 v[34:35], v[14:15], v[22:23], v[34:35]
	v_pk_mul_f32 v[36:37], v[32:33], s[58:59]
	v_pk_mul_f32 v[36:37], v[32:33], v[36:37]
	v_pk_fma_f32 v[36:37], v[32:33], v[36:37], v[32:33]
	v_pk_mul_f32 v[36:37], v[36:37], s[60:61]
	v_pk_mul_f32 v[36:37], v[36:37], s[68:69]
	v_exp_f32_e32 v38, v36
	v_exp_f32_e32 v39, v37
	s_nop 0
	v_pk_add_f32 v[38:39], v[38:39], s[82:83]
	v_rcp_f32_e32 v38, v38
	v_rcp_f32_e32 v39, v39
	s_nop 0
	v_pk_mul_f32 v[36:37], v[32:33], v[38:39]
	v_pk_mul_f32 v[36:37], v[34:35], v[36:37]
	v_cvt_pk_bf16_f32 v224, v36, v37
	global_store_dword v2, v224, s[66:67]
	s_add_u32 s66, s66, 0x2c00
	s_addc_u32 s67, s67, 0
	s_waitcnt vmcnt(20)
	v_lshlrev_b32_e32 v24, 16, v212
	v_and_b32_e32 v25, 0xffff0000, v212
	v_lshlrev_b32_e32 v26, 16, v213
	v_and_b32_e32 v27, 0xffff0000, v213
	v_pk_fma_f32 v[32:33], v[4:5], v[28:29], v[16:17]
	v_pk_fma_f32 v[34:35], v[6:7], v[30:31], v[18:19]
	v_pk_fma_f32 v[32:33], v[8:9], v[20:21], v[32:33]
	v_pk_fma_f32 v[34:35], v[10:11], v[22:23], v[34:35]
	v_pk_fma_f32 v[32:33], v[12:13], v[24:25], v[32:33]
	v_pk_fma_f32 v[34:35], v[14:15], v[26:27], v[34:35]
	v_pk_mul_f32 v[36:37], v[32:33], s[58:59]
	v_pk_mul_f32 v[36:37], v[32:33], v[36:37]
	v_pk_fma_f32 v[36:37], v[32:33], v[36:37], v[32:33]
	v_pk_mul_f32 v[36:37], v[36:37], s[60:61]
	v_pk_mul_f32 v[36:37], v[36:37], s[68:69]
	v_exp_f32_e32 v38, v36
	v_exp_f32_e32 v39, v37
	s_nop 0
	v_pk_add_f32 v[38:39], v[38:39], s[82:83]
	v_rcp_f32_e32 v38, v38
	v_rcp_f32_e32 v39, v39
	s_nop 0
	v_pk_mul_f32 v[36:37], v[32:33], v[38:39]
	v_pk_mul_f32 v[36:37], v[34:35], v[36:37]
	v_cvt_pk_bf16_f32 v224, v36, v37
	global_store_dword v2, v224, s[66:67]
	s_add_u32 s66, s66, 0x2c00
	s_addc_u32 s67, s67, 0
	s_waitcnt vmcnt(19)
	v_lshlrev_b32_e32 v28, 16, v214
	v_and_b32_e32 v29, 0xffff0000, v214
	v_lshlrev_b32_e32 v30, 16, v215
	v_and_b32_e32 v31, 0xffff0000, v215
	v_pk_fma_f32 v[32:33], v[4:5], v[20:21], v[16:17]
	v_pk_fma_f32 v[34:35], v[6:7], v[22:23], v[18:19]
	v_pk_fma_f32 v[32:33], v[8:9], v[24:25], v[32:33]
	v_pk_fma_f32 v[34:35], v[10:11], v[26:27], v[34:35]
	v_pk_fma_f32 v[32:33], v[12:13], v[28:29], v[32:33]
	v_pk_fma_f32 v[34:35], v[14:15], v[30:31], v[34:35]
	v_pk_mul_f32 v[36:37], v[32:33], s[58:59]
	v_pk_mul_f32 v[36:37], v[32:33], v[36:37]
	v_pk_fma_f32 v[36:37], v[32:33], v[36:37], v[32:33]
	v_pk_mul_f32 v[36:37], v[36:37], s[60:61]
	v_pk_mul_f32 v[36:37], v[36:37], s[68:69]
	v_exp_f32_e32 v38, v36
	v_exp_f32_e32 v39, v37
	s_nop 0
	v_pk_add_f32 v[38:39], v[38:39], s[82:83]
	v_rcp_f32_e32 v38, v38
	v_rcp_f32_e32 v39, v39
	s_nop 0
	v_pk_mul_f32 v[36:37], v[32:33], v[38:39]
	v_pk_mul_f32 v[36:37], v[34:35], v[36:37]
	v_cvt_pk_bf16_f32 v224, v36, v37
	global_store_dword v2, v224, s[66:67]
	s_add_u32 s66, s66, 0x2c00
	s_addc_u32 s67, s67, 0
	s_waitcnt vmcnt(18)
	v_lshlrev_b32_e32 v20, 16, v216
	v_and_b32_e32 v21, 0xffff0000, v216
	v_lshlrev_b32_e32 v22, 16, v217
	v_and_b32_e32 v23, 0xffff0000, v217
	v_pk_fma_f32 v[32:33], v[4:5], v[24:25], v[16:17]
	v_pk_fma_f32 v[34:35], v[6:7], v[26:27], v[18:19]
	v_pk_fma_f32 v[32:33], v[8:9], v[28:29], v[32:33]
	v_pk_fma_f32 v[34:35], v[10:11], v[30:31], v[34:35]
	v_pk_fma_f32 v[32:33], v[12:13], v[20:21], v[32:33]
	v_pk_fma_f32 v[34:35], v[14:15], v[22:23], v[34:35]
	v_pk_mul_f32 v[36:37], v[32:33], s[58:59]
	v_pk_mul_f32 v[36:37], v[32:33], v[36:37]
	v_pk_fma_f32 v[36:37], v[32:33], v[36:37], v[32:33]
	v_pk_mul_f32 v[36:37], v[36:37], s[60:61]
	v_pk_mul_f32 v[36:37], v[36:37], s[68:69]
	v_exp_f32_e32 v38, v36
	v_exp_f32_e32 v39, v37
	s_nop 0
	v_pk_add_f32 v[38:39], v[38:39], s[82:83]
	v_rcp_f32_e32 v38, v38
	v_rcp_f32_e32 v39, v39
	s_nop 0
	v_pk_mul_f32 v[36:37], v[32:33], v[38:39]
	v_pk_mul_f32 v[36:37], v[34:35], v[36:37]
	v_cvt_pk_bf16_f32 v224, v36, v37
	global_store_dword v2, v224, s[66:67]
	s_add_u32 s66, s66, 0x2c00
	s_addc_u32 s67, s67, 0
	s_waitcnt vmcnt(17)
	v_lshlrev_b32_e32 v24, 16, v218
	v_and_b32_e32 v25, 0xffff0000, v218
	v_lshlrev_b32_e32 v26, 16, v219
	v_and_b32_e32 v27, 0xffff0000, v219
	v_pk_fma_f32 v[32:33], v[4:5], v[28:29], v[16:17]
	v_pk_fma_f32 v[34:35], v[6:7], v[30:31], v[18:19]
	v_pk_fma_f32 v[32:33], v[8:9], v[20:21], v[32:33]
	v_pk_fma_f32 v[34:35], v[10:11], v[22:23], v[34:35]
	v_pk_fma_f32 v[32:33], v[12:13], v[24:25], v[32:33]
	v_pk_fma_f32 v[34:35], v[14:15], v[26:27], v[34:35]
	v_pk_mul_f32 v[36:37], v[32:33], s[58:59]
	v_pk_mul_f32 v[36:37], v[32:33], v[36:37]
	v_pk_fma_f32 v[36:37], v[32:33], v[36:37], v[32:33]
	v_pk_mul_f32 v[36:37], v[36:37], s[60:61]
	v_pk_mul_f32 v[36:37], v[36:37], s[68:69]
	v_exp_f32_e32 v38, v36
	v_exp_f32_e32 v39, v37
	s_nop 0
	v_pk_add_f32 v[38:39], v[38:39], s[82:83]
	v_rcp_f32_e32 v38, v38
	v_rcp_f32_e32 v39, v39
	s_nop 0
	v_pk_mul_f32 v[36:37], v[32:33], v[38:39]
	v_pk_mul_f32 v[36:37], v[34:35], v[36:37]
	v_cvt_pk_bf16_f32 v224, v36, v37
	global_store_dword v2, v224, s[66:67]
	s_add_u32 s66, s66, 0x2c00
	s_addc_u32 s67, s67, 0
	s_waitcnt vmcnt(16)
	v_lshlrev_b32_e32 v28, 16, v220
	v_and_b32_e32 v29, 0xffff0000, v220
	v_lshlrev_b32_e32 v30, 16, v221
	v_and_b32_e32 v31, 0xffff0000, v221
	v_pk_fma_f32 v[32:33], v[4:5], v[20:21], v[16:17]
	v_pk_fma_f32 v[34:35], v[6:7], v[22:23], v[18:19]
	v_pk_fma_f32 v[32:33], v[8:9], v[24:25], v[32:33]
	v_pk_fma_f32 v[34:35], v[10:11], v[26:27], v[34:35]
	v_pk_fma_f32 v[32:33], v[12:13], v[28:29], v[32:33]
	v_pk_fma_f32 v[34:35], v[14:15], v[30:31], v[34:35]
	v_pk_mul_f32 v[36:37], v[32:33], s[58:59]
	v_pk_mul_f32 v[36:37], v[32:33], v[36:37]
	v_pk_fma_f32 v[36:37], v[32:33], v[36:37], v[32:33]
	v_pk_mul_f32 v[36:37], v[36:37], s[60:61]
	v_pk_mul_f32 v[36:37], v[36:37], s[68:69]
	v_exp_f32_e32 v38, v36
	v_exp_f32_e32 v39, v37
	s_cmp_lg_u32 s1, 31
	s_cbranch_scc1 .Lact_ncs0
	s_lshr_b32 s6, s0, 5
	s_lshl_b32 s6, s6, 1
	s_mul_i32 s6, s6, 0x5800
	s_add_u32 s6, s3, s6
	s_addc_u32 s7, s21, 0
	global_store_dwordx2 v1, v[28:29], s[6:7]
	s_add_u32 s6, s6, 0x2c00
	s_addc_u32 s7, s7, 0
	global_store_dwordx2 v1, v[30:31], s[6:7]
; __device__ __forceinline__ float bf2f(unsigned b) { return __uint_as_float(b << 16); }
; __device__ __forceinline__ unsigned pk2(float lo, float hi) { unsigned r; asm("v_cvt_pk_bf16_f32 %0, %1, %2" : "=v"(r) : "v"(lo), "v"(hi)); return r; }
; __device__ __forceinline__ float gelu_t(float x) { return x * __builtin_amdgcn_rcpf(1.f + __expf(-1.5957691216057308f * (x + 0.044715f * x * x * x))); }
; __device__ __forceinline__ void act_item(int item, u16* UP, const u16* HALO, const float* sconv, const float* wconv, const float* bconv, float* out, int lane) {
;     ...
;         for (int t = 0; t < 16; ++t) {
;             const int row = rb * 64 + tb + t;
;             if (sample && (t & 3) == 0) { const int ns = (row - TP) >> 2; const float* s0 = sconv + (size_t)ns * 2 * FF2;
;                 const f32x2 a = *(const f32x2*)(s0 + j0), b = *(const f32x2*)(s0 + FF + j0), c = *(const f32x2*)(s0 + FF2 + j0), dd = *(const f32x2*)(s0 + FF2 + FF + j0);
;                 g2[0] = a.x; g2[1] = a.y; v2[0] = b.x; v2[1] = b.y; g1[0] = c.x; g1[1] = c.y; v1[0] = dd.x; v1[1] = dd.y; }
;             const float g0[2] = {bf2f(gw[t] & 0xffffu), bf2f(gw[t] >> 16)}, v0[2] = {bf2f(vw[t] & 0xffffu), bf2f(vw[t] >> 16)};
;             float res[2];
; #pragma unroll
;             for (int p = 0; p < 2; ++p) { const float cgv = bg[p] + wgt[0][p] * g2[p] + wgt[1][p] * g1[p] + wgt[2][p] * g0[p];
;                 const float cvv = bv[p] + wvl[0][p] * v2[p] + wvl[1][p] * v1[p] + wvl[2][p] * v0[p]; res[p] = gelu_t(cgv) * cvv;
;                 g2[p] = g1[p]; g1[p] = g0[p]; v2[p] = v1[p]; v1[p] = v0[p]; }
;             *(unsigned*)(UP + (size_t)row * FF2 + j0) = pk2(res[0], res[1]);
;             if (!sample) { const int tq = row & 2047; if (tq >= 2046) { float* o = out + O_CONVP + ((size_t)(row >> 11) * 2 + (tq - 2046)) * FF2;
;                     *(f32x2*)(o + j0) = (f32x2){g0[0], g0[1]}; *(f32x2*)(o + FF + j0) = (f32x2){v0[0], v0[1]}; } }
.Lact_ncs0:
	v_pk_add_f32 v[38:39], v[38:39], s[82:83]
	v_rcp_f32_e32 v38, v38
	v_rcp_f32_e32 v39, v39
	s_nop 0
	v_pk_mul_f32 v[36:37], v[32:33], v[38:39]
	v_pk_mul_f32 v[36:37], v[34:35], v[36:37]
	v_cvt_pk_bf16_f32 v224, v36, v37
	global_store_dword v2, v224, s[66:67]
	s_add_u32 s66, s66, 0x2c00
	s_addc_u32 s67, s67, 0
	s_waitcnt vmcnt(15)
	v_lshlrev_b32_e32 v20, 16, v222
	v_and_b32_e32 v21, 0xffff0000, v222
	v_lshlrev_b32_e32 v22, 16, v223
	v_and_b32_e32 v23, 0xffff0000, v223
	v_pk_fma_f32 v[32:33], v[4:5], v[24:25], v[16:17]
	v_pk_fma_f32 v[34:35], v[6:7], v[26:27], v[18:19]
	v_pk_fma_f32 v[32:33], v[8:9], v[28:29], v[32:33]
	v_pk_fma_f32 v[34:35], v[10:11], v[30:31], v[34:35]
	v_pk_fma_f32 v[32:33], v[12:13], v[20:21], v[32:33]
	v_pk_fma_f32 v[34:35], v[14:15], v[22:23], v[34:35]
	v_pk_mul_f32 v[36:37], v[32:33], s[58:59]
	v_pk_mul_f32 v[36:37], v[32:33], v[36:37]
	v_pk_fma_f32 v[36:37], v[32:33], v[36:37], v[32:33]
	v_pk_mul_f32 v[36:37], v[36:37], s[60:61]
	v_pk_mul_f32 v[36:37], v[36:37], s[68:69]
	v_exp_f32_e32 v38, v36
	v_exp_f32_e32 v39, v37
	s_cmp_lg_u32 s1, 31
	s_cbranch_scc1 .Lact_ncs1
	s_lshr_b32 s6, s0, 5
	s_lshl_b32 s6, s6, 1
	s_add_i32 s6, s6, 1
	s_mul_i32 s6, s6, 0x5800
	s_add_u32 s6, s3, s6
	s_addc_u32 s7, s21, 0
	global_store_dwordx2 v1, v[20:21], s[6:7]
	s_add_u32 s6, s6, 0x2c00
	s_addc_u32 s7, s7, 0
	global_store_dwordx2 v1, v[22:23], s[6:7]
.Lact_ncs1:
	v_pk_add_f32 v[38:39], v[38:39], s[82:83]
	v_rcp_f32_e32 v38, v38
	v_rcp_f32_e32 v39, v39
	s_nop 0
	v_pk_mul_f32 v[36:37], v[32:33], v[38:39]
	v_pk_mul_f32 v[36:37], v[34:35], v[36:37]
	v_cvt_pk_bf16_f32 v224, v36, v37
	global_store_dword v2, v224, s[66:67]
	s_add_u32 s66, s66, 0x2c00
	s_addc_u32 s67, s67, 0
	s_branch .LBB0_770
